# NSA: scale folded into q weights, Ot spilled to LDS across sel/win, reference max in MFMA C operand in the WINDOW loop only (sel loop keeps per-element add)
# speedup vs baseline: 1.0015x; 1.0015x over previous
.LBB0_235:
	v_lshlrev_b32_e32 v212, 4, v224
	ds_read_b128 v[34:37], v212 offset:32768
	ds_read_b128 v[38:41], v212 offset:36864
	ds_read_b128 v[42:45], v212 offset:40960
	ds_read_b128 v[46:49], v212 offset:45056
	ds_read_b128 v[50:53], v212 offset:50176
	ds_read_b128 v[54:57], v212 offset:54272
	ds_read_b128 v[58:61], v212 offset:58368
	ds_read_b128 v[62:65], v212 offset:62464
	s_waitcnt lgkmcnt(0)
	v_and_b32_e32 v0, 0xffff0000, v236
	v_mul_f32_e32 v0, 0xbfb8aa3b, v0
	v_exp_f32_e32 v200, v0
	s_waitcnt vmcnt(3)
	v_pk_add_f32 v[98:99], v[200:201], v[220:221]
	s_nop 0
	v_div_scale_f32 v0, s[0:1], v98, v98, 1.0
	v_rcp_f32_e32 v100, v0
	ds_bpermute_b32 v221, v235, v203
	v_fma_f32 v101, -v0, v100, 1.0
	v_fmac_f32_e32 v100, v101, v100
	v_div_scale_f32 v101, vcc, 1.0, v98, 1.0
	s_waitcnt vmcnt(2)
	v_mul_f32_e32 v102, v101, v100
	v_fma_f32 v103, -v0, v102, v101
	v_fmac_f32_e32 v102, v103, v100
	v_fma_f32 v0, -v0, v102, v101
	v_div_fmas_f32 v0, v0, v100, v102
	v_div_fixup_f32 v0, v0, v98, 1.0
	v_div_scale_f32 v98, s[0:1], v99, v99, v0
	v_rcp_f32_e32 v100, v98
	s_nop 0
	v_fma_f32 v101, -v98, v100, 1.0
	v_fmac_f32_e32 v100, v101, v100
	v_div_scale_f32 v101, vcc, v0, v99, v0
	v_mul_f32_e32 v102, v101, v100
	v_fma_f32 v103, -v98, v102, v101
	v_fmac_f32_e32 v102, v103, v100
	v_fma_f32 v98, -v98, v102, v101
	v_div_fmas_f32 v98, v98, v100, v102
	v_div_fixup_f32 v0, v98, v99, v0
	v_lshlrev_b32_e32 v98, 16, v236
	v_mul_f32_e32 v98, 0xbfb8aa3b, v98
	v_exp_f32_e32 v98, v98
	v_pk_mul_f32 v[82:83], v[82:83], v[0:1] op_sel_hi:[1,0]
	v_add_f32_e32 v98, 1.0, v98
	v_div_scale_f32 v99, s[0:1], v98, v98, 1.0
	v_rcp_f32_e32 v100, v99
	s_nop 0
	v_fma_f32 v101, -v99, v100, 1.0
	v_fmac_f32_e32 v100, v101, v100
	v_div_scale_f32 v101, vcc, 1.0, v98, 1.0
	v_mul_f32_e32 v102, v101, v100
	v_fma_f32 v103, -v99, v102, v101
	v_fmac_f32_e32 v102, v103, v100
	v_fma_f32 v99, -v99, v102, v101
	v_div_fmas_f32 v99, v99, v100, v102
	v_div_fixup_f32 v98, v99, v98, 1.0
	v_lshlrev_b32_e32 v99, 16, v202
	v_mul_f32_e32 v99, 0xbfb8aa3b, v99
	v_exp_f32_e32 v202, v99
	s_waitcnt lgkmcnt(0)
	v_pk_add_f32 v[100:101], v[202:203], v[220:221]
	s_nop 0
	v_div_scale_f32 v99, s[0:1], v100, v100, 1.0
	v_rcp_f32_e32 v102, v99
	s_nop 0
	v_fma_f32 v103, -v99, v102, 1.0
	v_fmac_f32_e32 v102, v103, v102
	v_div_scale_f32 v103, vcc, 1.0, v100, 1.0
	v_mul_f32_e32 v104, v103, v102
	v_fma_f32 v105, -v99, v104, v103
	v_fmac_f32_e32 v104, v105, v102
	v_fma_f32 v99, -v99, v104, v103
	v_div_fmas_f32 v99, v99, v102, v104
	v_div_fixup_f32 v99, v99, v100, 1.0
	v_div_scale_f32 v100, s[0:1], v101, v101, v99
	v_rcp_f32_e32 v102, v100
	v_pk_fma_f32 v[34:35], v[98:99], v[34:35], v[82:83] op_sel_hi:[0,1,1]
	v_fma_f32 v103, -v100, v102, 1.0
	v_fmac_f32_e32 v102, v103, v102
	v_div_scale_f32 v103, vcc, v99, v101, v99
	v_mul_f32_e32 v104, v103, v102
	v_fma_f32 v105, -v100, v104, v103
	v_fmac_f32_e32 v104, v105, v102
	v_fma_f32 v100, -v100, v104, v103
	v_div_fmas_f32 v100, v100, v102, v104
	v_div_fixup_f32 v100, v100, v101, v99
	v_pk_fma_f32 v[2:3], v[2:3], v[100:101], v[34:35] op_sel_hi:[1,0,1]
	v_pk_mul_f32 v[34:35], v[84:85], v[0:1] op_sel_hi:[1,0]
	v_cvt_pk_bf16_f32 v2, v2, v3
	v_pk_fma_f32 v[34:35], v[98:99], v[36:37], v[34:35] op_sel_hi:[0,1,1]
	v_pk_fma_f32 v[4:5], v[4:5], v[100:101], v[34:35] op_sel_hi:[1,0,1]
	v_pk_mul_f32 v[34:35], v[86:87], v[0:1] op_sel_hi:[1,0]
	v_cvt_pk_bf16_f32 v3, v4, v5
	v_pk_fma_f32 v[34:35], v[98:99], v[38:39], v[34:35] op_sel_hi:[0,1,1]
	v_pk_fma_f32 v[6:7], v[6:7], v[100:101], v[34:35] op_sel_hi:[1,0,1]
	v_pk_mul_f32 v[34:35], v[88:89], v[0:1] op_sel_hi:[1,0]
	s_nop 0
	v_pk_fma_f32 v[34:35], v[98:99], v[40:41], v[34:35] op_sel_hi:[0,1,1]
	v_pk_fma_f32 v[8:9], v[8:9], v[100:101], v[34:35] op_sel_hi:[1,0,1]
	v_pk_mul_f32 v[34:35], v[90:91], v[0:1] op_sel_hi:[1,0]
	s_nop 0
	v_pk_fma_f32 v[34:35], v[98:99], v[42:43], v[34:35] op_sel_hi:[0,1,1]
	v_pk_fma_f32 v[10:11], v[10:11], v[100:101], v[34:35] op_sel_hi:[1,0,1]
	v_pk_mul_f32 v[34:35], v[92:93], v[0:1] op_sel_hi:[1,0]
	s_nop 0
	v_pk_fma_f32 v[34:35], v[98:99], v[44:45], v[34:35] op_sel_hi:[0,1,1]
	v_pk_fma_f32 v[12:13], v[12:13], v[100:101], v[34:35] op_sel_hi:[1,0,1]
	v_pk_mul_f32 v[34:35], v[94:95], v[0:1] op_sel_hi:[1,0]
	s_nop 0
	v_pk_fma_f32 v[34:35], v[98:99], v[46:47], v[34:35] op_sel_hi:[0,1,1]
	v_pk_fma_f32 v[14:15], v[14:15], v[100:101], v[34:35] op_sel_hi:[1,0,1]
	v_pk_mul_f32 v[34:35], v[96:97], v[0:1] op_sel_hi:[1,0]
	s_nop 0
	v_pk_fma_f32 v[34:35], v[98:99], v[48:49], v[34:35] op_sel_hi:[0,1,1]
	v_pk_fma_f32 v[16:17], v[16:17], v[100:101], v[34:35] op_sel_hi:[1,0,1]
	v_pk_mul_f32 v[34:35], v[66:67], v[0:1] op_sel_hi:[1,0]
	s_nop 0
	v_pk_fma_f32 v[34:35], v[98:99], v[50:51], v[34:35] op_sel_hi:[0,1,1]
	v_pk_fma_f32 v[18:19], v[18:19], v[100:101], v[34:35] op_sel_hi:[1,0,1]
	v_pk_mul_f32 v[34:35], v[68:69], v[0:1] op_sel_hi:[1,0]
	s_nop 0
	v_pk_fma_f32 v[34:35], v[98:99], v[52:53], v[34:35] op_sel_hi:[0,1,1]
	v_pk_fma_f32 v[20:21], v[20:21], v[100:101], v[34:35] op_sel_hi:[1,0,1]
	v_pk_mul_f32 v[34:35], v[70:71], v[0:1] op_sel_hi:[1,0]
	s_nop 0
	v_pk_fma_f32 v[34:35], v[98:99], v[54:55], v[34:35] op_sel_hi:[0,1,1]
	v_pk_fma_f32 v[22:23], v[22:23], v[100:101], v[34:35] op_sel_hi:[1,0,1]
	v_pk_mul_f32 v[34:35], v[72:73], v[0:1] op_sel_hi:[1,0]
	s_nop 0
	v_pk_fma_f32 v[34:35], v[98:99], v[56:57], v[34:35] op_sel_hi:[0,1,1]
	v_pk_fma_f32 v[24:25], v[24:25], v[100:101], v[34:35] op_sel_hi:[1,0,1]
	v_pk_mul_f32 v[34:35], v[74:75], v[0:1] op_sel_hi:[1,0]
	s_nop 0
	v_pk_fma_f32 v[34:35], v[98:99], v[58:59], v[34:35] op_sel_hi:[0,1,1]
	v_pk_fma_f32 v[26:27], v[26:27], v[100:101], v[34:35] op_sel_hi:[1,0,1]
	v_pk_mul_f32 v[34:35], v[76:77], v[0:1] op_sel_hi:[1,0]
	s_nop 0
	v_pk_fma_f32 v[34:35], v[98:99], v[60:61], v[34:35] op_sel_hi:[0,1,1]
	v_pk_fma_f32 v[28:29], v[28:29], v[100:101], v[34:35] op_sel_hi:[1,0,1]
	v_pk_mul_f32 v[34:35], v[78:79], v[0:1] op_sel_hi:[1,0]
	s_nop 0
	v_pk_fma_f32 v[34:35], v[98:99], v[62:63], v[34:35] op_sel_hi:[0,1,1]
	v_pk_fma_f32 v[30:31], v[30:31], v[100:101], v[34:35] op_sel_hi:[1,0,1]
	v_pk_mul_f32 v[34:35], v[80:81], v[0:1] op_sel_hi:[1,0]
	v_lshlrev_b32_e32 v0, 1, v234
	v_pk_fma_f32 v[34:35], v[98:99], v[64:65], v[34:35] op_sel_hi:[0,1,1]
	v_pk_fma_f32 v[32:33], v[32:33], v[100:101], v[34:35] op_sel_hi:[1,0,1]
	v_lshlrev_b64 v[34:35], 11, v[198:199]
	v_lshl_add_u64 v[34:35], s[96:97], 0, v[34:35]
	v_lshl_add_u64 v[34:35], v[34:35], 0, v[0:1]
	v_lshlrev_b32_e32 v0, 1, v237
	v_lshl_add_u64 v[34:35], v[34:35], 0, v[0:1]
	global_store_dwordx2 v[34:35], v[2:3], off
	v_cvt_pk_bf16_f32 v2, v6, v7
	v_cvt_pk_bf16_f32 v3, v8, v9
	global_store_dwordx2 v[34:35], v[2:3], off offset:16
	v_cvt_pk_bf16_f32 v2, v10, v11
	v_cvt_pk_bf16_f32 v3, v12, v13
	global_store_dwordx2 v[34:35], v[2:3], off offset:32
	v_cvt_pk_bf16_f32 v2, v14, v15
	v_cvt_pk_bf16_f32 v3, v16, v17
	global_store_dwordx2 v[34:35], v[2:3], off offset:48
	v_cvt_pk_bf16_f32 v2, v18, v19
	v_cvt_pk_bf16_f32 v3, v20, v21
	global_store_dwordx2 v[34:35], v[2:3], off offset:64
	v_cvt_pk_bf16_f32 v2, v22, v23
	v_cvt_pk_bf16_f32 v3, v24, v25
	global_store_dwordx2 v[34:35], v[2:3], off offset:80
	v_cvt_pk_bf16_f32 v2, v26, v27
	v_cvt_pk_bf16_f32 v3, v28, v29
	global_store_dwordx2 v[34:35], v[2:3], off offset:96
	v_cvt_pk_bf16_f32 v2, v30, v31
	v_cvt_pk_bf16_f32 v3, v32, v33
	global_store_dwordx2 v[34:35], v[2:3], off offset:112

.LBB0_241:
	v_mov_b32_e32 v60, v2
	global_load_dwordx4 v[62:65], v[54:55], off
	global_load_dwordx4 v[94:97], v[52:53], off
	global_load_dwordx4 v[98:101], v[50:51], off
	global_load_dwordx4 v[2:5], v[48:49], off
	global_load_dwordx4 v[102:105], v[46:47], off offset:3072
	global_load_dwordx4 v[106:109], v[46:47], off offset:2048
	global_load_dwordx4 v[110:113], v[46:47], off offset:1024
	global_load_dwordx4 v[6:9], v[46:47], off
	v_add_u32_e32 v61, 0xfffffc50, v37
	v_cmp_le_i32_e32 vcc, v61, v200
	v_add_u32_e32 v61, 0xfffffe50, v37
	s_add_i32 s0, s1, 1
	s_cmp_lt_u32 s0, s12
	s_cselect_b32 s94, s0, s1
	s_mov_b32 s1, 0xff800000
	s_lshl_b64 s[14:15], s[94:95], 13
	s_add_u32 s14, s42, s14
	s_addc_u32 s15, s43, s15
	v_mov_b32_e32 v173, v1
	v_lshl_add_u64 v[48:49], s[14:15], 0, v[172:173]
	v_mov_b32_e32 v175, v1
	v_mov_b32_e32 v177, v1
	v_mov_b32_e32 v179, v1
	v_lshl_add_u64 v[46:47], s[14:15], 0, v[0:1]
	v_lshl_add_u64 v[50:51], s[14:15], 0, v[174:175]
	v_lshl_add_u64 v[52:53], s[14:15], 0, v[176:177]
	v_lshl_add_u64 v[54:55], s[14:15], 0, v[178:179]
	s_cmp_eq_u32 s12, s0
	s_waitcnt vmcnt(0)
	v_mfma_f32_32x32x16_bf16 v[18:33], v[6:9], v[90:93], 0
	v_mfma_f32_32x32x16_bf16 v[2:17], v[2:5], v[90:93], 0
	v_mfma_f32_32x32x16_bf16 v[18:33], v[110:113], v[130:133], v[18:33]
	v_mfma_f32_32x32x16_bf16 v[2:17], v[98:101], v[130:133], v[2:17]
	v_mfma_f32_32x32x16_bf16 v[18:33], v[106:109], v[134:137], v[18:33]
	v_mfma_f32_32x32x16_bf16 v[2:17], v[94:97], v[134:137], v[2:17]
	v_mfma_f32_32x32x16_bf16 v[18:33], v[102:105], v[138:141], v[18:33]
	v_mfma_f32_32x32x16_bf16 v[2:17], v[62:65], v[138:141], v[2:17]
	s_nop 10
	v_cndmask_b32_e32 v18, v222, v18, vcc
	v_cmp_le_i32_e32 vcc, v61, v200
	v_max_f32_e32 v62, v18, v18
	s_nop 0
	v_cndmask_b32_e32 v2, v222, v2, vcc
	v_max_f32_e32 v61, v2, v2
	v_max_f32_e32 v61, v62, v61
	v_add_u32_e32 v62, 0xfffffc60, v37
	v_cmp_le_i32_e32 vcc, v62, v200
	v_add_u32_e32 v62, 0xfffffe60, v37
	s_nop 0
	v_cndmask_b32_e32 v19, v222, v19, vcc
	v_cmp_le_i32_e32 vcc, v62, v200
	v_max_f32_e32 v63, v19, v19
	s_nop 0
	v_cndmask_b32_e32 v3, v222, v3, vcc
	v_max_f32_e32 v62, v3, v3
	v_max_f32_e32 v62, v63, v62
	v_max3_f32 v61, v61, s1, v62
	v_add_u32_e32 v62, 0xfffffc70, v37
	v_cmp_le_i32_e32 vcc, v62, v200
	v_add_u32_e32 v62, 0xfffffe70, v37
	s_mov_b32 s1, s0
	v_cndmask_b32_e32 v20, v222, v20, vcc
	v_cmp_le_i32_e32 vcc, v62, v200
	v_max_f32_e32 v63, v20, v20
	s_nop 0
	v_cndmask_b32_e32 v4, v222, v4, vcc
	v_max_f32_e32 v62, v4, v4
	v_max_f32_e32 v62, v63, v62
	v_add_u32_e32 v63, 0xfffffc80, v37
	v_cmp_le_i32_e32 vcc, v63, v200
	v_add_u32_e32 v63, 0xfffffe80, v37
	s_nop 0
	v_cndmask_b32_e32 v21, v222, v21, vcc
	v_cmp_le_i32_e32 vcc, v63, v200
	v_max_f32_e32 v64, v21, v21
	s_nop 0
	v_cndmask_b32_e32 v5, v222, v5, vcc
	v_max_f32_e32 v63, v5, v5
	v_max_f32_e32 v63, v64, v63
	v_max3_f32 v61, v61, v62, v63
	v_add_u32_e32 v62, 0xfffffcd0, v37
	v_cmp_le_i32_e32 vcc, v62, v200
	v_add_u32_e32 v62, 0xfffffed0, v37
	s_nop 0
	v_cndmask_b32_e32 v22, v222, v22, vcc
	v_cmp_le_i32_e32 vcc, v62, v200
	v_max_f32_e32 v63, v22, v22
	s_nop 0
	v_cndmask_b32_e32 v6, v222, v6, vcc
	v_max_f32_e32 v62, v6, v6
	v_max_f32_e32 v62, v63, v62
	v_add_u32_e32 v63, 0xfffffce0, v37
	v_cmp_le_i32_e32 vcc, v63, v200
	v_add_u32_e32 v63, 0xfffffee0, v37
	s_nop 0
	v_cndmask_b32_e32 v23, v222, v23, vcc
	v_cmp_le_i32_e32 vcc, v63, v200
	v_max_f32_e32 v64, v23, v23
	s_nop 0
	v_cndmask_b32_e32 v7, v222, v7, vcc
	v_max_f32_e32 v63, v7, v7
	v_max_f32_e32 v63, v64, v63
	v_max3_f32 v61, v61, v62, v63
	v_add_u32_e32 v62, 0xfffffcf0, v37
	v_cmp_le_i32_e32 vcc, v62, v200
	v_add_u32_e32 v62, 0xfffffef0, v37
	s_nop 0
	v_cndmask_b32_e32 v24, v222, v24, vcc
	v_cmp_le_i32_e32 vcc, v62, v200
	v_max_f32_e32 v63, v24, v24
	s_nop 0
	v_cndmask_b32_e32 v8, v222, v8, vcc
	v_max_f32_e32 v62, v8, v8
	v_max_f32_e32 v62, v63, v62
	v_add_u32_e32 v63, 0xfffffd00, v37
	v_cmp_le_i32_e32 vcc, v63, v200
	v_add_u32_e32 v63, 0xffffff00, v37
	s_nop 0
	v_cndmask_b32_e32 v25, v222, v25, vcc
	v_cmp_le_i32_e32 vcc, v63, v200
	v_max_f32_e32 v64, v25, v25
	s_nop 0
	v_cndmask_b32_e32 v9, v222, v9, vcc
	v_max_f32_e32 v63, v9, v9
	v_max_f32_e32 v63, v64, v63
	v_max3_f32 v61, v61, v62, v63
	v_add_u32_e32 v62, 0xfffffd50, v37
	v_cmp_le_i32_e32 vcc, v62, v200
	v_add_u32_e32 v62, 0xffffff50, v37
	s_nop 0
	v_cndmask_b32_e32 v26, v222, v26, vcc
	v_cmp_le_i32_e32 vcc, v62, v200
	v_max_f32_e32 v63, v26, v26
	s_nop 0
	v_cndmask_b32_e32 v10, v222, v10, vcc
	v_max_f32_e32 v62, v10, v10
	v_max_f32_e32 v62, v63, v62
	v_add_u32_e32 v63, 0xfffffd60, v37
	v_cmp_le_i32_e32 vcc, v63, v200
	v_add_u32_e32 v63, 0xffffff60, v37
	s_nop 0
	v_cndmask_b32_e32 v27, v222, v27, vcc
	v_cmp_le_i32_e32 vcc, v63, v200
	v_max_f32_e32 v64, v27, v27
	s_nop 0
	v_cndmask_b32_e32 v11, v222, v11, vcc
	v_max_f32_e32 v63, v11, v11
	v_max_f32_e32 v63, v64, v63
	v_max3_f32 v61, v61, v62, v63
	v_add_u32_e32 v62, 0xfffffd70, v37
	v_cmp_le_i32_e32 vcc, v62, v200
	v_add_u32_e32 v62, 0xffffff70, v37
	s_nop 0
	v_cndmask_b32_e32 v28, v222, v28, vcc
	v_cmp_le_i32_e32 vcc, v62, v200
	v_max_f32_e32 v63, v28, v28
	s_nop 0
	v_cndmask_b32_e32 v12, v222, v12, vcc
	v_max_f32_e32 v62, v12, v12
	v_max_f32_e32 v62, v63, v62
	v_add_u32_e32 v63, 0xfffffd80, v37
	v_cmp_le_i32_e32 vcc, v63, v200
	v_add_u32_e32 v63, 0xffffff80, v37
	s_nop 0
	v_cndmask_b32_e32 v29, v222, v29, vcc
	v_cmp_le_i32_e32 vcc, v63, v200
	v_max_f32_e32 v64, v29, v29
	s_nop 0
	v_cndmask_b32_e32 v13, v222, v13, vcc
	v_max_f32_e32 v63, v13, v13
	v_max_f32_e32 v63, v64, v63
	v_max3_f32 v61, v61, v62, v63
	v_add_u32_e32 v62, 0xfffffdd0, v37
	v_cmp_le_i32_e32 vcc, v62, v200
	v_subrev_u32_e32 v62, 48, v37
	s_nop 0
	v_cndmask_b32_e32 v30, v222, v30, vcc
	v_cmp_le_i32_e32 vcc, v62, v200
	v_max_f32_e32 v63, v30, v30
	s_nop 0
	v_cndmask_b32_e32 v14, v222, v14, vcc
	v_max_f32_e32 v62, v14, v14
	v_max_f32_e32 v62, v63, v62
	v_add_u32_e32 v63, 0xfffffde0, v37
	v_cmp_le_i32_e32 vcc, v63, v200
	v_subrev_u32_e32 v63, 32, v37
	s_nop 0
	v_cndmask_b32_e32 v31, v222, v31, vcc
	v_cmp_le_i32_e32 vcc, v63, v200
	v_max_f32_e32 v64, v31, v31
	s_nop 0
	v_cndmask_b32_e32 v15, v222, v15, vcc
	v_max_f32_e32 v63, v15, v15
	v_max_f32_e32 v63, v64, v63
	v_max3_f32 v61, v61, v62, v63
	v_add_u32_e32 v62, 0xfffffdf0, v37
	v_cmp_le_i32_e32 vcc, v62, v200
	v_add_u32_e32 v62, -16, v37
	s_nop 0
	v_cndmask_b32_e32 v32, v222, v32, vcc
	v_cmp_le_i32_e32 vcc, v62, v200
	v_max_f32_e32 v63, v32, v32
	s_nop 0
	v_cndmask_b32_e32 v16, v222, v16, vcc
	v_max_f32_e32 v62, v16, v16
	v_max_f32_e32 v62, v63, v62
	v_add_u32_e32 v63, 0xfffffe00, v37
	v_cmp_le_i32_e32 vcc, v63, v200
	s_nop 1
	v_cndmask_b32_e32 v33, v222, v33, vcc
	v_cmp_le_i32_e32 vcc, v37, v200
	v_max_f32_e32 v64, v33, v33
	v_add_u32_e32 v37, 0x400, v37
	v_cndmask_b32_e32 v17, v222, v17, vcc
	v_max_f32_e32 v63, v17, v17
	v_max_f32_e32 v63, v64, v63
	v_max3_f32 v61, v61, v62, v63
	ds_bpermute_b32 v62, v235, v61
	s_waitcnt lgkmcnt(0)
	v_max3_f32 v61, v59, v61, v62
	v_sub_f32_e32 v173, 0, v61
	v_add_f32_e32 v18, v18, v173
	v_add_f32_e32 v2, v2, v173
	v_exp_f32_e32 v18, v18
	v_exp_f32_e32 v2, v2
	v_add_f32_e32 v3, v3, v173
	v_exp_f32_e32 v3, v3
	v_add_f32_e32 v4, v4, v173
	v_add_f32_e32 v2, v18, v2
	v_add_f32_e32 v18, v19, v173
	v_exp_f32_e32 v18, v18
	v_add_f32_e32 v2, 0, v2
	v_exp_f32_e32 v4, v4
	v_sub_f32_e32 v59, v59, v61
	v_add_f32_e32 v3, v18, v3
	v_add_f32_e32 v2, v3, v2
	v_add_f32_e32 v3, v20, v173
	v_exp_f32_e32 v3, v3
	v_exp_f32_e32 v59, v59
	v_add_f32_e32 v3, v3, v4
	v_add_f32_e32 v2, v3, v2
	v_add_f32_e32 v3, v21, v173
	v_add_f32_e32 v4, v5, v173
	v_exp_f32_e32 v3, v3
	v_exp_f32_e32 v4, v4
	s_nop 0
	v_add_f32_e32 v3, v3, v4
	v_add_f32_e32 v18, v3, v2
	v_add_f32_e32 v2, v22, v173
	v_exp_f32_e32 v3, v2
	v_add_f32_e32 v2, v6, v173
	v_exp_f32_e32 v5, v2
	v_add_f32_e32 v2, v23, v173
	v_add_f32_e32 v4, v7, v173
	v_exp_f32_e32 v2, v2
	v_exp_f32_e32 v4, v4
	s_nop 0
	v_pk_add_f32 v[2:3], v[2:3], v[4:5]
	s_nop 0
	v_add_f32_e32 v3, v3, v18
	v_add_f32_e32 v6, v2, v3
	v_add_f32_e32 v2, v24, v173
	v_exp_f32_e32 v3, v2
	v_add_f32_e32 v2, v8, v173
	v_exp_f32_e32 v5, v2
	v_add_f32_e32 v2, v25, v173
	v_add_f32_e32 v4, v9, v173
	v_exp_f32_e32 v2, v2
	v_exp_f32_e32 v4, v4
	s_nop 0
	v_pk_add_f32 v[2:3], v[2:3], v[4:5]
	s_nop 0
	v_add_f32_e32 v3, v3, v6
	v_add_f32_e32 v6, v2, v3
	v_add_f32_e32 v2, v26, v173
	v_exp_f32_e32 v3, v2
	v_add_f32_e32 v2, v10, v173
	v_exp_f32_e32 v5, v2
	v_add_f32_e32 v2, v27, v173
	v_add_f32_e32 v4, v11, v173
	v_exp_f32_e32 v2, v2
	v_exp_f32_e32 v4, v4
	s_nop 0
	v_pk_add_f32 v[2:3], v[2:3], v[4:5]
	s_nop 0
	v_add_f32_e32 v3, v3, v6
	v_add_f32_e32 v6, v2, v3
	v_add_f32_e32 v2, v28, v173
	v_exp_f32_e32 v3, v2
	v_add_f32_e32 v2, v12, v173
	v_exp_f32_e32 v5, v2
	v_add_f32_e32 v2, v29, v173
	v_add_f32_e32 v4, v13, v173
	v_exp_f32_e32 v2, v2
	v_exp_f32_e32 v4, v4
	s_nop 0
	v_pk_add_f32 v[2:3], v[2:3], v[4:5]
	s_nop 0
	v_add_f32_e32 v3, v3, v6
	v_add_f32_e32 v6, v2, v3
	v_add_f32_e32 v2, v30, v173
	v_exp_f32_e32 v3, v2
	v_add_f32_e32 v2, v14, v173
	v_exp_f32_e32 v5, v2
	v_add_f32_e32 v2, v31, v173
	v_add_f32_e32 v4, v15, v173
	v_exp_f32_e32 v2, v2
	v_exp_f32_e32 v4, v4
	s_nop 0
	v_pk_add_f32 v[2:3], v[2:3], v[4:5]
	s_nop 0
	v_add_f32_e32 v3, v3, v6
	v_add_f32_e32 v6, v2, v3
	v_add_f32_e32 v2, v32, v173
	v_exp_f32_e32 v3, v2
	v_add_f32_e32 v2, v16, v173
	v_exp_f32_e32 v5, v2
	v_add_f32_e32 v2, v33, v173
	v_add_f32_e32 v4, v17, v173
	v_exp_f32_e32 v2, v2
	v_exp_f32_e32 v4, v4
	s_nop 0
	v_pk_add_f32 v[2:3], v[2:3], v[4:5]
	s_nop 0
	v_add_f32_e32 v3, v3, v6
	v_add_f32_e32 v2, v2, v3
	v_fmac_f32_e32 v2, v60, v59
	v_mov_b32_e32 v59, v61
	s_cbranch_scc0 .LBB0_241
	global_load_dwordx4 v[114:117], v[34:35], off
	global_load_dwordx4 v[94:97], v[34:35], off offset:1024
	global_load_dwordx4 v[98:101], v[34:35], off offset:2048
	global_load_dwordx4 v[102:105], v[34:35], off offset:3072
	global_load_dwordx4 v[106:109], v[38:39], off
	global_load_dwordx4 v[110:113], v[40:41], off
	global_load_dwordx4 v[118:121], v[42:43], off
	global_load_dwordx4 v[122:125], v[44:45], off
	ds_bpermute_b32 v3, v235, v2
	v_lshlrev_b32_e32 v237, 2, v188
	s_lshl_b32 s14, s12, 4
	v_mov_b32_e32 v34, 0
	v_mov_b32_e32 v37, v1
	s_waitcnt lgkmcnt(0)
	v_add_f32_e32 v2, v2, v3
	v_div_scale_f32 v3, s[0:1], v2, v2, 1.0
	v_rcp_f32_e32 v4, v3
	s_mov_b32 s0, 0x8000
	v_readlane_b32 s1, v255, 0
	s_mov_b32 s13, 0
	v_fma_f32 v5, -v3, v4, 1.0
	v_fmac_f32_e32 v4, v5, v4
	v_div_scale_f32 v5, vcc, 1.0, v2, 1.0
	v_mul_f32_e32 v6, v5, v4
	v_fma_f32 v7, -v3, v6, v5
	v_fmac_f32_e32 v6, v7, v4
	v_fma_f32 v3, -v3, v6, v5
	v_div_fmas_f32 v3, v3, v4, v6
	v_div_fixup_f32 v3, v3, v2, 1.0
	v_cmp_lt_f32_e32 vcc, 0, v2
	v_mov_b32_e32 v171, v200
	s_mov_b32 s15, 0
	v_cndmask_b32_e32 v180, 0, v3, vcc
	v_cmp_lt_i32_e32 vcc, v252, v214
	v_mov_b32_e32 v181, v180
	v_mov_b32_e32 v35, v34
	v_cndmask_b32_e32 v2, v225, v252, vcc
	v_cmp_lt_i32_e32 vcc, v223, v214
	v_lshlrev_b32_e32 v175, 2, v2
	v_mov_b32_e32 v38, v34
	v_cndmask_b32_e32 v2, v225, v223, vcc
	v_lshlrev_b32_e32 v177, 2, v2
	v_lshl_add_u32 v2, v56, 9, v58
	v_add3_u32 v179, v2, v237, s0
	s_lshl_b32 s0, s86, 16
	s_add_u32 s0, s1, s0
	v_readlane_b32 s1, v255, 1
	s_addc_u32 s1, s1, 0
	v_cmp_eq_u32_e32 vcc, 0, v57
	v_lshl_add_u64 v[182:183], s[0:1], 0, v[36:37]
	v_mov_b32_e32 v36, v34
	v_mov_b32_e32 v37, v34
	v_mov_b32_e32 v39, v34
	v_mov_b32_e32 v40, v34
	v_mov_b32_e32 v41, v34
	v_mov_b32_e32 v42, v34
	v_mov_b32_e32 v43, v34
	v_mov_b32_e32 v44, v34
	v_mov_b32_e32 v45, v34
	v_mov_b32_e32 v46, v34
	v_mov_b32_e32 v47, v34
	v_mov_b32_e32 v48, v34
	v_mov_b32_e32 v49, v34
	v_mov_b32_e32 v50, v34
	v_mov_b32_e32 v51, v34
	v_mov_b32_e32 v52, v34
	v_mov_b32_e32 v53, v34
	v_mov_b32_e32 v54, v34
	v_mov_b32_e32 v55, v34
	v_mov_b32_e32 v56, v34
	v_mov_b32_e32 v57, v34
	v_mov_b32_e32 v58, v34
	v_mov_b32_e32 v59, v34
	v_mov_b32_e32 v60, v34
	v_mov_b32_e32 v61, v34
	v_mov_b32_e32 v62, v34
	v_mov_b32_e32 v63, v34
	v_mov_b32_e32 v64, v34
	v_mov_b32_e32 v65, v34
	s_branch .LBB0_244

.LBB0_244:
	s_waitcnt vmcnt(7)
	v_mfma_f32_32x32x16_bf16 v[18:33], v[114:117], v[90:93], 0
	s_mov_b32 s0, s15
	s_add_i32 s15, s15, 1
	s_cmp_lt_u32 s15, s12
	s_waitcnt vmcnt(1) lgkmcnt(0)
	v_mov_b64_e32 v[192:193], v[120:121]
	s_cselect_b32 s94, s15, s0
	v_mov_b64_e32 v[190:191], v[118:119]
	v_mov_b64_e32 v[120:121], v[104:105]
	v_mfma_f32_32x32x16_bf16 v[18:33], v[94:97], v[130:133], v[18:33]
	s_lshl_b64 s[0:1], s[94:95], 13
	v_mov_b64_e32 v[118:119], v[102:103]
	v_add_co_u32_e64 v102, s[40:41], s33, v182
	s_add_u32 s0, s42, s0
	v_mov_b64_e32 v[218:219], v[112:113]
	v_addc_co_u32_e64 v103, s[40:41], 0, v183, s[40:41]
	v_mfma_f32_32x32x16_bf16 v[18:33], v[98:101], v[134:137], v[18:33]
	s_addc_u32 s1, s43, s1
	v_mov_b64_e32 v[216:217], v[110:111]
	global_load_dwordx4 v[166:169], v[182:183], off
	global_load_dwordx4 v[162:165], v[182:183], off offset:1024
	global_load_dwordx4 v[158:161], v[182:183], off offset:2048
	global_load_dwordx4 v[142:145], v[182:183], off offset:3072
	global_load_dwordx4 v[150:153], v[102:103], off
	global_load_dwordx4 v[154:157], v[102:103], off offset:1024
	global_load_dwordx4 v[146:149], v[102:103], off offset:2048
	global_load_dwordx4 v[126:129], v[102:103], off offset:3072
	s_waitcnt vmcnt(8)
	v_mov_b64_e32 v[206:207], v[124:125]
	v_mov_b64_e32 v[204:205], v[122:123]
	v_or_b32_e32 v189, 47, v170
	v_mfma_f32_32x32x16_bf16 v[2:17], v[106:109], v[90:93], 0
	global_load_dwordx4 v[114:117], v0, s[0:1]
	global_load_dwordx4 v[94:97], v0, s[0:1] offset:1024
	global_load_dwordx4 v[98:101], v0, s[0:1] offset:2048
	global_load_dwordx4 v[102:105], v0, s[0:1] offset:3072
	global_load_dwordx4 v[106:109], v172, s[0:1]
	global_load_dwordx4 v[110:113], v174, s[0:1]
	v_or_b32_e32 v196, 31, v170
	v_cmp_le_i32_e64 s[40:41], v189, v171
	v_add_u32_e32 v189, 63, v170
	v_mfma_f32_32x32x16_bf16 v[18:33], v[118:121], v[138:141], v[18:33]
	global_load_dwordx4 v[118:121], v176, s[0:1]
	global_load_dwordx4 v[122:125], v178, s[0:1]
	v_mfma_f32_32x32x16_bf16 v[2:17], v[216:219], v[130:133], v[2:17]
	s_nop 8
	v_add_f32_e32 v18, v18, v173
	v_add_f32_e32 v19, v19, v173
	v_exp_f32_e32 v18, v18
	v_exp_f32_e32 v19, v19
	v_add_f32_e32 v21, v21, v173
	v_pk_mul_f32 v[194:195], v[180:181], v[18:19]
	v_add_f32_e32 v19, v20, v173
	v_exp_f32_e32 v19, v19
	v_mfma_f32_32x32x16_bf16 v[2:17], v[190:193], v[134:137], v[2:17]
	v_exp_f32_e32 v190, v21
	v_cndmask_b32_e64 v18, 0, v195, s[40:41]
	v_cmp_le_i32_e64 s[40:41], v196, v200
	v_mul_f32_e32 v19, v180, v19
	s_nop 0
	v_cndmask_b32_e64 v20, 0, v194, s[40:41]
	v_cmp_le_i32_e64 s[40:41], v189, v200
	v_mul_f32_e32 v189, v180, v190
	v_mfma_f32_32x32x16_bf16 v[2:17], v[204:207], v[138:141], v[2:17]
	v_cndmask_b32_e64 v21, 0, v19, s[40:41]
	v_add_u32_e32 v19, 0x4f, v170
	v_cmp_le_i32_e64 s[40:41], v19, v200
	v_add_f32_e32 v19, v20, v18
	s_nop 0
	v_cndmask_b32_e64 v189, 0, v189, s[40:41]
	v_add_f32_e32 v190, v21, v189
	v_add_f32_e32 v19, v19, v190
	ds_bpermute_b32 v190, v175, v19
	ds_bpermute_b32 v191, v175, v189
	s_waitcnt lgkmcnt(1)
	v_add_f32_e32 v193, v19, v190
	s_waitcnt lgkmcnt(0)
	v_add_f32_e32 v191, v189, v191
	ds_bpermute_b32 v197, v177, v193
	ds_bpermute_b32 v192, v177, v191
	v_mov_b32_e32 v19, v170
	v_add_u32_e32 v190, s13, v188
	s_and_saveexec_b64 s[0:1], vcc
	s_cbranch_execz .LBB0_247
	s_waitcnt lgkmcnt(1)
	v_add_f32_e32 v193, v193, v197
	ds_add_f32 v179, v193
	v_cmp_gt_u32_e64 s[40:41], s17, v190
	s_and_b64 exec, exec, s[40:41]
	s_cbranch_execz .LBB0_247
	s_waitcnt lgkmcnt(1)
	v_add_f32_e32 v191, v191, v192
	ds_add_f32 v179, v191 offset:4
.LBB0_247:
	s_or_b64 exec, exec, s[0:1]
	v_add_f32_e32 v22, v22, v173
	v_add_f32_e32 v23, v23, v173
	v_exp_f32_e32 v22, v22
	v_exp_f32_e32 v23, v23
	v_add_f32_e32 v25, v25, v173
	v_or_b32_e32 v191, 0xaf, v19
	v_exp_f32_e32 v25, v25
	s_waitcnt lgkmcnt(0)
	v_pk_mul_f32 v[192:193], v[180:181], v[22:23]
	v_add_f32_e32 v23, v24, v173
	v_exp_f32_e32 v24, v23
	v_or_b32_e32 v194, 0x9f, v170
	v_cmp_le_i32_e64 s[40:41], v191, v171
	v_add_u32_e32 v191, 0xbf, v170
	v_mul_f32_e32 v24, v180, v24
	v_cndmask_b32_e64 v22, 0, v193, s[40:41]
	v_cmp_le_i32_e64 s[40:41], v194, v200
	v_mul_f32_e32 v25, v180, v25
	s_nop 0
	v_cndmask_b32_e64 v23, 0, v192, s[40:41]
	v_cmp_le_i32_e64 s[40:41], v191, v200
	v_add_u32_e32 v191, 0xcf, v170
	s_nop 0
	v_cndmask_b32_e64 v24, 0, v24, s[40:41]
	v_cmp_le_i32_e64 s[40:41], v191, v200
	v_add_f32_e32 v191, v23, v22
	s_nop 0
	v_cndmask_b32_e64 v25, 0, v25, s[40:41]
	v_add_f32_e32 v192, v24, v25
	v_add_f32_e32 v191, v191, v192
	ds_bpermute_b32 v192, v175, v191
	ds_bpermute_b32 v194, v175, v25
	s_waitcnt lgkmcnt(1)
	v_add_f32_e32 v193, v191, v192
	s_waitcnt lgkmcnt(0)
	v_add_f32_e32 v191, v25, v194
	ds_bpermute_b32 v197, v177, v193
	ds_bpermute_b32 v192, v177, v191
	s_and_saveexec_b64 s[0:1], vcc
	s_cbranch_execz .LBB0_250
	s_waitcnt lgkmcnt(1)
	v_add_f32_e32 v193, v193, v197
	ds_add_f32 v179, v193 offset:8
	v_add_u32_e32 v193, 2, v190
	v_cmp_gt_u32_e64 s[40:41], s17, v193
	s_and_b64 exec, exec, s[40:41]
	s_cbranch_execz .LBB0_250
	s_waitcnt lgkmcnt(1)
	v_add_f32_e32 v191, v191, v192
	ds_add_f32 v179, v191 offset:12
.LBB0_250:
	s_or_b64 exec, exec, s[0:1]
	v_add_f32_e32 v26, v26, v173
	v_add_f32_e32 v27, v27, v173
	v_exp_f32_e32 v26, v26
	v_exp_f32_e32 v27, v27
	v_add_f32_e32 v29, v29, v173
	v_or_b32_e32 v191, 0x12f, v19
	v_exp_f32_e32 v29, v29
	s_waitcnt lgkmcnt(0)
	v_pk_mul_f32 v[192:193], v[180:181], v[26:27]
	v_add_f32_e32 v27, v28, v173
	v_exp_f32_e32 v28, v27
	v_or_b32_e32 v194, 0x11f, v170
	v_cmp_le_i32_e64 s[40:41], v191, v171
	v_add_u32_e32 v191, 0x13f, v170
	v_mul_f32_e32 v28, v180, v28
	v_cndmask_b32_e64 v26, 0, v193, s[40:41]
	v_cmp_le_i32_e64 s[40:41], v194, v200
	v_mul_f32_e32 v29, v180, v29
	s_nop 0
	v_cndmask_b32_e64 v27, 0, v192, s[40:41]
	v_cmp_le_i32_e64 s[40:41], v191, v200
	v_add_u32_e32 v191, 0x14f, v170
	s_nop 0
	v_cndmask_b32_e64 v28, 0, v28, s[40:41]
	v_cmp_le_i32_e64 s[40:41], v191, v200
	v_add_f32_e32 v191, v27, v26
	s_nop 0
	v_cndmask_b32_e64 v29, 0, v29, s[40:41]
	v_add_f32_e32 v192, v28, v29
	v_add_f32_e32 v191, v191, v192
	ds_bpermute_b32 v192, v175, v191
	ds_bpermute_b32 v194, v175, v29
	s_waitcnt lgkmcnt(1)
	v_add_f32_e32 v193, v191, v192
	s_waitcnt lgkmcnt(0)
	v_add_f32_e32 v191, v29, v194
	ds_bpermute_b32 v197, v177, v193
	ds_bpermute_b32 v192, v177, v191
	s_and_saveexec_b64 s[0:1], vcc
	s_cbranch_execz .LBB0_253
	s_waitcnt lgkmcnt(1)
	v_add_f32_e32 v193, v193, v197
	ds_add_f32 v179, v193 offset:16
	v_add_u32_e32 v193, 4, v190
	v_cmp_gt_u32_e64 s[40:41], s17, v193
	s_and_b64 exec, exec, s[40:41]
	s_cbranch_execz .LBB0_253
	s_waitcnt lgkmcnt(1)
	v_add_f32_e32 v191, v191, v192
	ds_add_f32 v179, v191 offset:20
.LBB0_253:
	s_or_b64 exec, exec, s[0:1]
	v_add_f32_e32 v30, v30, v173
	v_add_f32_e32 v31, v31, v173
	v_exp_f32_e32 v30, v30
	v_exp_f32_e32 v31, v31
	v_add_f32_e32 v33, v33, v173
	v_or_b32_e32 v191, 0x1af, v19
	v_exp_f32_e32 v33, v33
	s_waitcnt lgkmcnt(0)
	v_pk_mul_f32 v[192:193], v[180:181], v[30:31]
	v_add_f32_e32 v31, v32, v173
	v_exp_f32_e32 v32, v31
	v_or_b32_e32 v194, 0x19f, v170
	v_cmp_le_i32_e64 s[40:41], v191, v171
	v_add_u32_e32 v191, 0x1bf, v170
	v_mul_f32_e32 v32, v180, v32
	v_cndmask_b32_e64 v30, 0, v193, s[40:41]
	v_cmp_le_i32_e64 s[40:41], v194, v200
	v_mul_f32_e32 v33, v180, v33
	s_nop 0
	v_cndmask_b32_e64 v31, 0, v192, s[40:41]
	v_cmp_le_i32_e64 s[40:41], v191, v200
	v_add_u32_e32 v191, 0x1cf, v170
	s_nop 0
	v_cndmask_b32_e64 v32, 0, v32, s[40:41]
	v_cmp_le_i32_e64 s[40:41], v191, v200
	v_add_f32_e32 v191, v31, v30
	s_nop 0
	v_cndmask_b32_e64 v33, 0, v33, s[40:41]
	v_add_f32_e32 v192, v32, v33
	v_add_f32_e32 v191, v191, v192
	ds_bpermute_b32 v192, v175, v191
	ds_bpermute_b32 v194, v175, v33
	s_waitcnt lgkmcnt(1)
	v_add_f32_e32 v193, v191, v192
	s_waitcnt lgkmcnt(0)
	v_add_f32_e32 v191, v33, v194
	ds_bpermute_b32 v197, v177, v193
	ds_bpermute_b32 v192, v177, v191
	s_and_saveexec_b64 s[0:1], vcc
	s_cbranch_execz .LBB0_256
	s_waitcnt lgkmcnt(1)
	v_add_f32_e32 v193, v193, v197
	ds_add_f32 v179, v193 offset:24
	v_add_u32_e32 v193, 6, v190
	v_cmp_gt_u32_e64 s[40:41], s17, v193
	s_and_b64 exec, exec, s[40:41]
	s_cbranch_execz .LBB0_256
	s_waitcnt lgkmcnt(1)
	v_add_f32_e32 v191, v191, v192
	ds_add_f32 v179, v191 offset:28
.LBB0_256:
	s_or_b64 exec, exec, s[0:1]
	v_add_f32_e32 v2, v2, v173
	v_add_f32_e32 v3, v3, v173
	v_exp_f32_e32 v2, v2
	v_exp_f32_e32 v3, v3
	v_add_f32_e32 v5, v5, v173
	v_or_b32_e32 v191, 0x22f, v19
	v_exp_f32_e32 v5, v5
	s_waitcnt lgkmcnt(0)
	v_pk_mul_f32 v[192:193], v[180:181], v[2:3]
	v_add_f32_e32 v3, v4, v173
	v_exp_f32_e32 v4, v3
	v_or_b32_e32 v194, 0x21f, v170
	v_cmp_le_i32_e64 s[40:41], v191, v171
	v_add_u32_e32 v191, 0x23f, v170
	v_mul_f32_e32 v4, v180, v4
	v_cndmask_b32_e64 v2, 0, v193, s[40:41]
	v_cmp_le_i32_e64 s[40:41], v194, v200
	v_mul_f32_e32 v5, v180, v5
	s_nop 0
	v_cndmask_b32_e64 v3, 0, v192, s[40:41]
	v_cmp_le_i32_e64 s[40:41], v191, v200
	v_add_u32_e32 v191, 0x24f, v170
	s_nop 0
	v_cndmask_b32_e64 v4, 0, v4, s[40:41]
	v_cmp_le_i32_e64 s[40:41], v191, v200
	v_add_f32_e32 v191, v3, v2
	s_nop 0
	v_cndmask_b32_e64 v5, 0, v5, s[40:41]
	v_add_f32_e32 v192, v4, v5
	v_add_f32_e32 v191, v191, v192
	ds_bpermute_b32 v192, v175, v191
	ds_bpermute_b32 v194, v175, v5
	s_waitcnt lgkmcnt(1)
	v_add_f32_e32 v193, v191, v192
	s_waitcnt lgkmcnt(0)
	v_add_f32_e32 v191, v5, v194
	ds_bpermute_b32 v197, v177, v193
	ds_bpermute_b32 v192, v177, v191
	s_and_saveexec_b64 s[0:1], vcc
	s_cbranch_execz .LBB0_259
	s_waitcnt lgkmcnt(1)
	v_add_f32_e32 v193, v193, v197
	ds_add_f32 v179, v193 offset:32
	v_add_u32_e32 v193, 8, v190
	v_cmp_gt_u32_e64 s[40:41], s17, v193
	s_and_b64 exec, exec, s[40:41]
	s_cbranch_execz .LBB0_259
	s_waitcnt lgkmcnt(1)
	v_add_f32_e32 v191, v191, v192
	ds_add_f32 v179, v191 offset:36
.LBB0_259:
	s_or_b64 exec, exec, s[0:1]
	v_add_f32_e32 v6, v6, v173
	v_add_f32_e32 v7, v7, v173
	v_exp_f32_e32 v6, v6
	v_exp_f32_e32 v7, v7
	v_add_f32_e32 v9, v9, v173
	v_or_b32_e32 v191, 0x2af, v19
	v_exp_f32_e32 v9, v9
	s_waitcnt lgkmcnt(0)
	v_pk_mul_f32 v[192:193], v[180:181], v[6:7]
	v_add_f32_e32 v7, v8, v173
	v_exp_f32_e32 v8, v7
	v_or_b32_e32 v194, 0x29f, v170
	v_cmp_le_i32_e64 s[40:41], v191, v171
	v_add_u32_e32 v191, 0x2bf, v170
	v_mul_f32_e32 v8, v180, v8
	v_cndmask_b32_e64 v6, 0, v193, s[40:41]
	v_cmp_le_i32_e64 s[40:41], v194, v200
	v_mul_f32_e32 v9, v180, v9
	s_nop 0
	v_cndmask_b32_e64 v7, 0, v192, s[40:41]
	v_cmp_le_i32_e64 s[40:41], v191, v200
	v_add_u32_e32 v191, 0x2cf, v170
	s_nop 0
	v_cndmask_b32_e64 v8, 0, v8, s[40:41]
	v_cmp_le_i32_e64 s[40:41], v191, v200
	v_add_f32_e32 v191, v7, v6
	s_nop 0
	v_cndmask_b32_e64 v9, 0, v9, s[40:41]
	v_add_f32_e32 v192, v8, v9
	v_add_f32_e32 v191, v191, v192
	ds_bpermute_b32 v192, v175, v191
	ds_bpermute_b32 v194, v175, v9
	s_waitcnt lgkmcnt(1)
	v_add_f32_e32 v193, v191, v192
	s_waitcnt lgkmcnt(0)
	v_add_f32_e32 v191, v9, v194
	ds_bpermute_b32 v197, v177, v193
	ds_bpermute_b32 v192, v177, v191
	s_and_saveexec_b64 s[0:1], vcc
	s_cbranch_execz .LBB0_262
	s_waitcnt lgkmcnt(1)
	v_add_f32_e32 v193, v193, v197
	ds_add_f32 v179, v193 offset:40
	v_add_u32_e32 v193, 10, v190
	v_cmp_gt_u32_e64 s[40:41], s17, v193
	s_and_b64 exec, exec, s[40:41]
	s_cbranch_execz .LBB0_262
	s_waitcnt lgkmcnt(1)
	v_add_f32_e32 v191, v191, v192
	ds_add_f32 v179, v191 offset:44
.LBB0_262:
	s_or_b64 exec, exec, s[0:1]
	v_add_f32_e32 v10, v10, v173
	v_add_f32_e32 v11, v11, v173
	v_exp_f32_e32 v10, v10
	v_exp_f32_e32 v11, v11
	v_add_f32_e32 v13, v13, v173
	v_or_b32_e32 v191, 0x32f, v19
	v_exp_f32_e32 v13, v13
	s_waitcnt lgkmcnt(0)
	v_pk_mul_f32 v[192:193], v[180:181], v[10:11]
	v_add_f32_e32 v11, v12, v173
	v_exp_f32_e32 v12, v11
	v_or_b32_e32 v194, 0x31f, v170
	v_cmp_le_i32_e64 s[40:41], v191, v171
	v_add_u32_e32 v191, 0x33f, v170
	v_mul_f32_e32 v12, v180, v12
	v_cndmask_b32_e64 v10, 0, v193, s[40:41]
	v_cmp_le_i32_e64 s[40:41], v194, v200
	v_mul_f32_e32 v13, v180, v13
	s_nop 0
	v_cndmask_b32_e64 v11, 0, v192, s[40:41]
	v_cmp_le_i32_e64 s[40:41], v191, v200
	v_add_u32_e32 v191, 0x34f, v170
	s_nop 0
	v_cndmask_b32_e64 v12, 0, v12, s[40:41]
	v_cmp_le_i32_e64 s[40:41], v191, v200
	v_add_f32_e32 v191, v11, v10
	s_nop 0
	v_cndmask_b32_e64 v13, 0, v13, s[40:41]
	v_add_f32_e32 v192, v12, v13
	v_add_f32_e32 v191, v191, v192
	ds_bpermute_b32 v192, v175, v191
	ds_bpermute_b32 v194, v175, v13
	s_waitcnt lgkmcnt(1)
	v_add_f32_e32 v193, v191, v192
	s_waitcnt lgkmcnt(0)
	v_add_f32_e32 v191, v13, v194
	ds_bpermute_b32 v197, v177, v193
	ds_bpermute_b32 v192, v177, v191
	s_and_saveexec_b64 s[0:1], vcc
	s_cbranch_execz .LBB0_265
	s_waitcnt lgkmcnt(1)
	v_add_f32_e32 v193, v193, v197
	ds_add_f32 v179, v193 offset:48
	v_add_u32_e32 v193, 12, v190
	v_cmp_gt_u32_e64 s[40:41], s17, v193
	s_and_b64 exec, exec, s[40:41]
	s_cbranch_execz .LBB0_265
	s_waitcnt lgkmcnt(1)
	v_add_f32_e32 v191, v191, v192
	ds_add_f32 v179, v191 offset:52
.LBB0_265:
	s_or_b64 exec, exec, s[0:1]
	v_add_f32_e32 v14, v14, v173
	v_add_f32_e32 v15, v15, v173
	v_exp_f32_e32 v14, v14
	v_exp_f32_e32 v15, v15
	v_add_f32_e32 v17, v17, v173
	v_or_b32_e32 v19, 0x3af, v19
	v_exp_f32_e32 v17, v17
	s_waitcnt lgkmcnt(0)
	v_pk_mul_f32 v[192:193], v[180:181], v[14:15]
	v_add_f32_e32 v15, v16, v173
	v_exp_f32_e32 v16, v15
	v_or_b32_e32 v191, 0x39f, v170
	v_cmp_le_i32_e64 s[40:41], v19, v171
	v_add_u32_e32 v19, 0x3bf, v170
	v_mul_f32_e32 v16, v180, v16
	v_cndmask_b32_e64 v14, 0, v193, s[40:41]
	v_cmp_le_i32_e64 s[40:41], v191, v200
	v_mul_f32_e32 v17, v180, v17
	s_nop 0
	v_cndmask_b32_e64 v15, 0, v192, s[40:41]
	v_cmp_le_i32_e64 s[40:41], v19, v200
	v_add_u32_e32 v19, 0x3cf, v170
	s_nop 0
	v_cndmask_b32_e64 v16, 0, v16, s[40:41]
	v_cmp_le_i32_e64 s[40:41], v19, v200
	v_add_f32_e32 v19, v15, v14
	s_nop 0
	v_cndmask_b32_e64 v17, 0, v17, s[40:41]
	v_add_f32_e32 v191, v16, v17
	v_add_f32_e32 v19, v19, v191
	ds_bpermute_b32 v191, v175, v19
	ds_bpermute_b32 v193, v175, v17
	s_waitcnt lgkmcnt(1)
	v_add_f32_e32 v192, v19, v191
	s_waitcnt lgkmcnt(0)
	v_add_f32_e32 v19, v17, v193
	ds_bpermute_b32 v193, v177, v192
	ds_bpermute_b32 v191, v177, v19
	s_and_saveexec_b64 s[0:1], vcc
	s_cbranch_execz .LBB0_243
	s_waitcnt lgkmcnt(1)
	v_add_f32_e32 v192, v192, v193
	ds_add_f32 v179, v192 offset:56
	v_add_u32_e32 v190, 14, v190
	v_cmp_gt_u32_e64 s[40:41], s17, v190
	s_and_b64 exec, exec, s[40:41]
	s_cbranch_execz .LBB0_243
	s_waitcnt lgkmcnt(1)
	v_add_f32_e32 v19, v19, v191
	ds_add_f32 v179, v19 offset:60
	s_branch .LBB0_243

.LBB0_388:
	s_or_b64 exec, exec, s[0:1]
	s_add_i32 s43, s80, 1
	v_mov_b32_e32 v6, v224
	s_mov_b32 s14, 0
	s_waitcnt lgkmcnt(0)
	s_barrier
	v_lshlrev_b32_e32 v212, 4, v224
	ds_write_b128 v212, v[34:37] offset:32768
	ds_write_b128 v212, v[38:41] offset:36864
	ds_write_b128 v212, v[42:45] offset:40960
	ds_write_b128 v212, v[46:49] offset:45056
	ds_write_b128 v212, v[50:53] offset:50176
	ds_write_b128 v212, v[54:57] offset:54272
	ds_write_b128 v212, v[58:61] offset:58368
	ds_write_b128 v212, v[62:65] offset:62464
	s_branch .LBB0_390

.LBB0_405:
	s_cmp_eq_u32 s101, 0
	s_cbranch_scc1 .Lmy_lazy_0
	v_max3_f32 v169, v18, v19, v20
	v_max3_f32 v171, v21, v22, v23
	v_max3_f32 v172, v24, v25, v26
	v_max3_f32 v169, v169, v27, v28
	v_max3_f32 v171, v171, v29, v30
	v_max3_f32 v172, v172, v31, v32
	v_max3_f32 v169, v169, v171, v33
	v_max_f32_e32 v169, v169, v172
	v_max3_f32 v171, v2, v3, v4
	v_max3_f32 v172, v5, v6, v7
	v_max3_f32 v173, v8, v9, v10
	v_max3_f32 v171, v171, v11, v12
	v_max3_f32 v172, v172, v13, v14
	v_max3_f32 v173, v173, v15, v16
	v_max3_f32 v171, v171, v172, v17
	v_max3_f32 v169, v169, v171, v173
	v_cndmask_b32_e64 v169, v222, v169, s[40:41]
	v_mov_b32_e32 v171, v169
	s_nop 1
	v_permlane32_swap_b32_e32 v169, v171
	v_max3_f32 v169, v170, v169, v171
	v_add_f32_e32 v171, 0x41000000, v170
	v_cmp_gt_f32_e32 vcc, v169, v171
	s_cbranch_vccz .Lmy_lazy_0
	v_sub_f32_e32 v170, v170, v169
	v_exp_f32_e32 v170, v170
	s_nop 0
	v_mul_f32_e32 v201, v201, v170
	v_pk_mul_f32 v[80:81], v[80:81], v[170:171] op_sel_hi:[1,0]
	v_pk_mul_f32 v[78:79], v[78:79], v[170:171] op_sel_hi:[1,0]
	v_pk_mul_f32 v[76:77], v[76:77], v[170:171] op_sel_hi:[1,0]
	v_pk_mul_f32 v[74:75], v[74:75], v[170:171] op_sel_hi:[1,0]
	v_pk_mul_f32 v[72:73], v[72:73], v[170:171] op_sel_hi:[1,0]
	v_pk_mul_f32 v[70:71], v[70:71], v[170:171] op_sel_hi:[1,0]
	v_pk_mul_f32 v[68:69], v[68:69], v[170:171] op_sel_hi:[1,0]
	v_pk_mul_f32 v[66:67], v[66:67], v[170:171] op_sel_hi:[1,0]
	v_pk_mul_f32 v[96:97], v[96:97], v[170:171] op_sel_hi:[1,0]
	v_pk_mul_f32 v[94:95], v[94:95], v[170:171] op_sel_hi:[1,0]
	v_pk_mul_f32 v[92:93], v[92:93], v[170:171] op_sel_hi:[1,0]
	v_pk_mul_f32 v[90:91], v[90:91], v[170:171] op_sel_hi:[1,0]
	v_pk_mul_f32 v[88:89], v[88:89], v[170:171] op_sel_hi:[1,0]
	v_pk_mul_f32 v[86:87], v[86:87], v[170:171] op_sel_hi:[1,0]
	v_pk_mul_f32 v[84:85], v[84:85], v[170:171] op_sel_hi:[1,0]
	v_pk_mul_f32 v[82:83], v[82:83], v[170:171] op_sel_hi:[1,0]
	s_branch .LBB0_407

.LBB0_407:
	v_sub_f32_e32 v170, 0, v169
	v_cndmask_b32_e64 v170, v222, v170, s[40:41]
	v_add_f32_e32 v18, v18, v170
	v_add_f32_e32 v2, v2, v170
	v_exp_f32_e32 v18, v18
	v_exp_f32_e32 v2, v2
	v_add_f32_e32 v19, v19, v170
	v_add_f32_e32 v3, v3, v170
	v_exp_f32_e32 v19, v19
	v_exp_f32_e32 v3, v3
	v_add_f32_e32 v177, v18, v2
	v_add_f32_e32 v20, v20, v170
	v_add_f32_e32 v4, v4, v170
	v_exp_f32_e32 v20, v20
	v_exp_f32_e32 v4, v4
	v_add_f32_e32 v176, v19, v3
	v_add_f32_e32 v177, v176, v177
	v_add_f32_e32 v21, v21, v170
	v_add_f32_e32 v5, v5, v170
	v_exp_f32_e32 v21, v21
	v_exp_f32_e32 v5, v5
	v_add_f32_e32 v176, v20, v4
	v_add_f32_e32 v177, v176, v177
	v_add_f32_e32 v22, v22, v170
	v_add_f32_e32 v6, v6, v170
	v_exp_f32_e32 v22, v22
	v_exp_f32_e32 v6, v6
	v_add_f32_e32 v176, v21, v5
	v_add_f32_e32 v177, v176, v177
	v_add_f32_e32 v23, v23, v170
	v_add_f32_e32 v7, v7, v170
	v_exp_f32_e32 v23, v23
	v_exp_f32_e32 v7, v7
	v_add_f32_e32 v176, v22, v6
	v_add_f32_e32 v177, v176, v177
	v_add_f32_e32 v24, v24, v170
	v_add_f32_e32 v8, v8, v170
	v_exp_f32_e32 v24, v24
	v_exp_f32_e32 v8, v8
	v_add_f32_e32 v176, v23, v7
	v_add_f32_e32 v177, v176, v177
	v_add_f32_e32 v25, v25, v170
	v_add_f32_e32 v9, v9, v170
	v_exp_f32_e32 v25, v25
	v_exp_f32_e32 v9, v9
	v_add_f32_e32 v176, v24, v8
	v_add_f32_e32 v177, v176, v177
	v_add_f32_e32 v26, v26, v170
	v_add_f32_e32 v10, v10, v170
	v_exp_f32_e32 v26, v26
	v_exp_f32_e32 v10, v10
	v_add_f32_e32 v176, v25, v9
	v_add_f32_e32 v177, v176, v177
	v_add_f32_e32 v27, v27, v170
	v_add_f32_e32 v11, v11, v170
	v_exp_f32_e32 v27, v27
	v_exp_f32_e32 v11, v11
	v_add_f32_e32 v176, v26, v10
	v_add_f32_e32 v177, v176, v177
	v_add_f32_e32 v28, v28, v170
	v_add_f32_e32 v12, v12, v170
	v_exp_f32_e32 v28, v28
	v_exp_f32_e32 v12, v12
	v_add_f32_e32 v176, v27, v11
	v_add_f32_e32 v177, v176, v177
	v_add_f32_e32 v29, v29, v170
	v_add_f32_e32 v13, v13, v170
	v_exp_f32_e32 v29, v29
	v_exp_f32_e32 v13, v13
	v_add_f32_e32 v176, v28, v12
	v_add_f32_e32 v177, v176, v177
	v_add_f32_e32 v30, v30, v170
	v_add_f32_e32 v14, v14, v170
	v_exp_f32_e32 v30, v30
	v_exp_f32_e32 v14, v14
	v_add_f32_e32 v176, v29, v13
	v_add_f32_e32 v177, v176, v177
	v_add_f32_e32 v31, v31, v170
	v_add_f32_e32 v15, v15, v170
	v_exp_f32_e32 v31, v31
	v_exp_f32_e32 v15, v15
	v_add_f32_e32 v176, v30, v14
	v_add_f32_e32 v177, v176, v177
	v_add_f32_e32 v32, v32, v170
	v_add_f32_e32 v16, v16, v170
	v_exp_f32_e32 v32, v32
	v_exp_f32_e32 v16, v16
	v_add_f32_e32 v176, v31, v15
	v_add_f32_e32 v177, v176, v177
	v_add_f32_e32 v33, v33, v170
	v_add_f32_e32 v17, v17, v170
	v_exp_f32_e32 v33, v33
	v_exp_f32_e32 v17, v17
	v_add_f32_e32 v176, v32, v16
	v_add_f32_e32 v177, v176, v177
	v_add_f32_e32 v176, v33, v17
	v_add_f32_e32 v177, v176, v177
	v_cmp_lt_f32_e32 vcc, 0x47800000, v177
	s_cbranch_vccnz .Lmy_rd_s

.LBB0_410:
	ds_bpermute_b32 v221, v235, v201
	s_sub_i32 s1, 0x1de1, s77
	s_max_i32 s1, s1, 0
	s_lshl_b32 s0, s86, 19
	s_lshr_b32 s94, s1, 6
	v_mov_b32_e32 v0, v224
	v_mov_b32_e32 v33, 0
	s_cmp_gt_u32 s94, s80
	v_mov_b32_e32 v32, 0
	v_mov_b32_e32 v31, 0
	v_mov_b32_e32 v30, 0
	v_mov_b32_e32 v29, 0
	v_mov_b32_e32 v28, 0
	v_mov_b32_e32 v27, 0
	v_mov_b32_e32 v26, 0
	v_mov_b32_e32 v25, 0
	v_mov_b32_e32 v24, 0
	v_mov_b32_e32 v23, 0
	v_mov_b32_e32 v22, 0
	v_mov_b32_e32 v21, 0
	v_mov_b32_e32 v20, 0
	v_mov_b32_e32 v19, 0
	v_mov_b32_e32 v18, 0
	v_mov_b32_e32 v17, 0
	v_mov_b32_e32 v16, 0
	v_mov_b32_e32 v15, 0
	v_mov_b32_e32 v14, 0
	v_mov_b32_e32 v13, 0
	v_mov_b32_e32 v12, 0
	v_mov_b32_e32 v11, 0
	v_mov_b32_e32 v10, 0
	v_mov_b32_e32 v9, 0
	v_mov_b32_e32 v8, 0
	v_mov_b32_e32 v7, 0
	v_mov_b32_e32 v6, 0
	v_mov_b32_e32 v5, 0
	v_mov_b32_e32 v4, 0
	v_mov_b32_e32 v3, 0
	v_mov_b32_e32 v2, 0
	v_mov_b32_e32 v203, 0
	s_waitcnt lgkmcnt(0)
	s_barrier
	s_cbranch_scc1 .LBB0_235
	s_lshl_b32 s0, s0, 1
	v_readlane_b32 s1, v254, 58
	s_add_u32 s12, s1, s0
	v_readlane_b32 s1, v254, 59
	s_addc_u32 s13, s1, 0
	v_readlane_b32 s1, v254, 60
	v_lshlrev_b32_e32 v2, 3, v0
	s_add_u32 s14, s1, s0
	v_readlane_b32 s0, v254, 61
	v_ashrrev_i32_e32 v3, 31, v2
	s_addc_u32 s15, s0, 0
	s_lshl_b64 s[0:1], s[94:95], 13
	v_lshlrev_b64 v[204:205], 1, v[2:3]
	v_add_u32_e32 v2, 0x800, v2
	s_add_u32 s12, s12, s0
	v_ashrrev_i32_e32 v3, 31, v2
	s_addc_u32 s13, s13, s1
	v_lshlrev_b64 v[206:207], 1, v[2:3]
	v_lshl_add_u64 v[4:5], s[12:13], 0, v[204:205]
	v_lshl_add_u64 v[2:3], s[12:13], 0, v[206:207]
	s_add_u32 s12, s14, s0
	s_addc_u32 s13, s15, s1
	global_load_dwordx4 v[146:149], v[4:5], off
	global_load_dwordx4 v[150:153], v[2:3], off
	v_lshl_add_u64 v[2:3], s[12:13], 0, v[204:205]
	v_lshl_add_u64 v[4:5], s[12:13], 0, v[206:207]
	global_load_dwordx4 v[154:157], v[2:3], off
	global_load_dwordx4 v[158:161], v[4:5], off
	s_add_i32 s12, s46, 0xfffffe07
	s_lshl_b32 s13, s94, 6
	s_add_u32 s0, s42, s0
	v_lshlrev_b32_e32 v238, 4, v0
	v_lshrrev_b32_e32 v0, 3, v0
	s_addc_u32 s1, 0, s1
	v_readlane_b32 s14, v254, 62
	v_mov_b32_e32 v2, v1
	v_mov_b32_e32 v3, v1
	v_mov_b32_e32 v4, v1
	v_mov_b32_e32 v5, v1
	v_mov_b32_e32 v6, v1
	v_mov_b32_e32 v7, v1
	v_mov_b32_e32 v8, v1
	v_mov_b32_e32 v9, v1
	v_mov_b32_e32 v10, v1
	v_mov_b32_e32 v11, v1
	v_mov_b32_e32 v12, v1
	v_mov_b32_e32 v13, v1
	v_mov_b32_e32 v14, v1
	v_mov_b32_e32 v15, v1
	v_mov_b32_e32 v16, v1
	v_mov_b32_e32 v17, v1
	v_mov_b32_e32 v18, v1
	v_mov_b32_e32 v19, v1
	v_mov_b32_e32 v20, v1
	v_mov_b32_e32 v21, v1
	v_mov_b32_e32 v22, v1
	v_mov_b32_e32 v23, v1
	v_mov_b32_e32 v24, v1
	v_mov_b32_e32 v25, v1
	v_mov_b32_e32 v26, v1
	v_mov_b32_e32 v27, v1
	v_mov_b32_e32 v28, v1
	v_mov_b32_e32 v29, v1
	v_mov_b32_e32 v30, v1
	v_mov_b32_e32 v31, v1
	v_and_b32_e32 v240, 4, v0
	v_readlane_b32 s15, v254, 63
	s_add_u32 s0, s14, s0
	v_mov_b32_e32 v0, v1
	v_mov_b64_e32 v[32:33], v[30:31]
	v_and_b32_e32 v239, 0x3f0, v238
	v_add_u32_e32 v241, 0xfffffe00, v200
	s_addc_u32 s1, s15, s1
	s_mov_b32 s14, 0
	v_mov_b32_e32 v203, 0
	v_mov_b32_e32 v242, 0xf149f2ca
	v_mov_b64_e32 v[30:31], v[28:29]
	v_mov_b64_e32 v[28:29], v[26:27]
	v_mov_b64_e32 v[26:27], v[24:25]
	v_mov_b64_e32 v[24:25], v[22:23]
	v_mov_b64_e32 v[22:23], v[20:21]
	v_mov_b64_e32 v[20:21], v[18:19]
	v_mov_b64_e32 v[18:19], v[16:17]
	v_mov_b64_e32 v[16:17], v[14:15]
	v_mov_b64_e32 v[14:15], v[12:13]
	v_mov_b64_e32 v[12:13], v[10:11]
	v_mov_b64_e32 v[10:11], v[8:9]
	v_mov_b64_e32 v[8:9], v[6:7]
	v_mov_b64_e32 v[6:7], v[4:5]
	v_mov_b64_e32 v[4:5], v[2:3]
	v_mov_b64_e32 v[2:3], v[0:1]
	s_waitcnt vmcnt(0)
	ds_write_b128 v238, v[146:149]
	ds_write_b128 v238, v[150:153] offset:4096
	ds_write_b128 v238, v[154:157] offset:8192
	ds_write_b128 v238, v[158:161] offset:12288
	s_mov_b32 s100, 0
	v_mov_b32_e32 v212, 0
	v_mov_b32_e32 v34, 0
	v_mov_b32_e32 v35, 0
	v_mov_b32_e32 v36, 0
	v_mov_b32_e32 v37, 0
	v_mov_b32_e32 v38, 0
	v_mov_b32_e32 v39, 0
	v_mov_b32_e32 v40, 0
	v_mov_b32_e32 v41, 0
	v_mov_b32_e32 v42, 0
	v_mov_b32_e32 v43, 0
	v_mov_b32_e32 v44, 0
	v_mov_b32_e32 v45, 0
	v_mov_b32_e32 v46, 0
	v_mov_b32_e32 v47, 0
	v_mov_b32_e32 v48, 0
	v_mov_b32_e32 v49, 0
	s_mov_b32 s101, 1

.LBB0_414:
	v_add_u32_e32 v0, s15, v239
	ds_read_b128 v[98:101], v0
	ds_read_b128 v[162:165], v0 offset:1024
	ds_read_b128 v[166:169], v0 offset:2048
	ds_read_b128 v[170:173], v0 offset:3072
	ds_read_b128 v[102:105], v0 offset:4096
	ds_read_b128 v[174:177], v0 offset:5120
	ds_read_b128 v[178:181], v0 offset:6144
	ds_read_b128 v[216:219], v0 offset:7168
	s_waitcnt lgkmcnt(7)
	v_mfma_f32_32x32x16_bf16 v[114:129], v[98:101], v[142:145], v[34:49]
	s_waitcnt lgkmcnt(3)
	v_mfma_f32_32x32x16_bf16 v[98:113], v[102:105], v[142:145], v[34:49]
	v_mfma_f32_32x32x16_bf16 v[114:129], v[162:165], v[130:133], v[114:129]
	s_waitcnt lgkmcnt(2)
	v_mfma_f32_32x32x16_bf16 v[98:113], v[174:177], v[130:133], v[98:113]
	v_mfma_f32_32x32x16_bf16 v[114:129], v[166:169], v[134:137], v[114:129]
	s_waitcnt lgkmcnt(1)
	v_mfma_f32_32x32x16_bf16 v[98:113], v[178:181], v[134:137], v[98:113]
	v_mfma_f32_32x32x16_bf16 v[114:129], v[170:173], v[138:141], v[114:129]
	ds_read_b128 v[190:193], v0 offset:8192
	ds_read_b128 v[186:189], v0 offset:9216
	ds_read_b128 v[182:185], v0 offset:10240
	ds_read_b128 v[178:181], v0 offset:11264
	ds_read_b128 v[174:177], v0 offset:12288
	ds_read_b128 v[170:173], v0 offset:13312
	ds_read_b128 v[166:169], v0 offset:14336
	ds_read_b128 v[162:165], v0 offset:15360
	s_waitcnt lgkmcnt(8)
	v_mfma_f32_32x32x16_bf16 v[98:113], v[216:219], v[138:141], v[98:113]
	s_add_i32 s15, s13, 63
	s_cmp_le_i32 s15, s46
	s_cselect_b64 s[40:41], -1, 0
	s_cmp_gt_i32 s13, s12
	s_cselect_b64 s[42:43], -1, 0
	s_and_b64 s[40:41], s[40:41], s[42:43]
	s_and_b64 vcc, exec, s[40:41]
	s_cbranch_vccnz .LBB0_416
	v_add_u32_e32 v0, s13, v240
	v_add_u32_e32 v194, 32, v0
	v_cmp_le_i32_e32 vcc, v0, v200
	v_cmp_gt_i32_e64 s[42:43], v0, v241
	v_cmp_le_i32_e64 s[40:41], v194, v200
	s_and_b64 vcc, vcc, s[42:43]
	v_cmp_gt_i32_e64 s[42:43], v194, v241
	s_and_b64 s[40:41], s[40:41], s[42:43]
	v_cndmask_b32_e32 v114, v222, v114, vcc
	v_add_u32_e32 v194, 33, v0
	v_cmp_lt_i32_e32 vcc, v0, v200
	v_cmp_ge_i32_e64 s[42:43], v0, v241
	v_cndmask_b32_e64 v98, v222, v98, s[40:41]
	v_cmp_le_i32_e64 s[40:41], v194, v200
	s_and_b64 vcc, vcc, s[42:43]
	v_cmp_gt_i32_e64 s[42:43], v194, v241
	v_add_u32_e32 v194, 2, v0
	s_and_b64 s[40:41], s[40:41], s[42:43]
	v_cndmask_b32_e32 v115, v222, v115, vcc
	v_add_u32_e32 v195, 34, v0
	v_cmp_le_i32_e32 vcc, v194, v200
	v_cmp_gt_i32_e64 s[42:43], v194, v241
	v_cndmask_b32_e64 v99, v222, v99, s[40:41]
	v_cmp_le_i32_e64 s[40:41], v195, v200
	s_and_b64 vcc, vcc, s[42:43]
	v_cmp_gt_i32_e64 s[42:43], v195, v241
	v_add_u32_e32 v194, 3, v0
	s_and_b64 s[40:41], s[40:41], s[42:43]
	v_cndmask_b32_e32 v116, v222, v116, vcc
	v_add_u32_e32 v195, 35, v0
	v_cmp_le_i32_e32 vcc, v194, v200
	v_cmp_gt_i32_e64 s[42:43], v194, v241
	v_cndmask_b32_e64 v100, v222, v100, s[40:41]
	v_cmp_le_i32_e64 s[40:41], v195, v200
	s_and_b64 vcc, vcc, s[42:43]
	v_cmp_gt_i32_e64 s[42:43], v195, v241
	v_add_u32_e32 v194, 8, v0
	s_and_b64 s[40:41], s[40:41], s[42:43]
	v_cndmask_b32_e32 v117, v222, v117, vcc
	v_add_u32_e32 v195, 40, v0
	v_cmp_le_i32_e32 vcc, v194, v200
	v_cmp_gt_i32_e64 s[42:43], v194, v241
	v_cndmask_b32_e64 v101, v222, v101, s[40:41]
	v_cmp_le_i32_e64 s[40:41], v195, v200
	s_and_b64 vcc, vcc, s[42:43]
	v_cmp_gt_i32_e64 s[42:43], v195, v241
	v_add_u32_e32 v194, 9, v0
	s_and_b64 s[40:41], s[40:41], s[42:43]
	v_cndmask_b32_e32 v118, v222, v118, vcc
	v_add_u32_e32 v195, 41, v0
	v_cmp_le_i32_e32 vcc, v194, v200
	v_cmp_gt_i32_e64 s[42:43], v194, v241
	v_cndmask_b32_e64 v102, v222, v102, s[40:41]
	v_cmp_le_i32_e64 s[40:41], v195, v200
	s_and_b64 vcc, vcc, s[42:43]
	v_cmp_gt_i32_e64 s[42:43], v195, v241
	v_add_u32_e32 v194, 10, v0
	s_and_b64 s[40:41], s[40:41], s[42:43]
	v_cndmask_b32_e32 v119, v222, v119, vcc
	v_add_u32_e32 v195, 42, v0
	v_cmp_le_i32_e32 vcc, v194, v200
	v_cmp_gt_i32_e64 s[42:43], v194, v241
	v_cndmask_b32_e64 v103, v222, v103, s[40:41]
	v_cmp_le_i32_e64 s[40:41], v195, v200
	s_and_b64 vcc, vcc, s[42:43]
	v_cmp_gt_i32_e64 s[42:43], v195, v241
	v_add_u32_e32 v194, 11, v0
	s_and_b64 s[40:41], s[40:41], s[42:43]
	v_cndmask_b32_e32 v120, v222, v120, vcc
	v_add_u32_e32 v195, 43, v0
	v_cmp_le_i32_e32 vcc, v194, v200
	v_cmp_gt_i32_e64 s[42:43], v194, v241
	v_cndmask_b32_e64 v104, v222, v104, s[40:41]
	v_cmp_le_i32_e64 s[40:41], v195, v200
	s_and_b64 vcc, vcc, s[42:43]
	v_cmp_gt_i32_e64 s[42:43], v195, v241
	v_add_u32_e32 v194, 16, v0
	s_and_b64 s[40:41], s[40:41], s[42:43]
	v_cndmask_b32_e32 v121, v222, v121, vcc
	v_add_u32_e32 v195, 48, v0
	v_cmp_le_i32_e32 vcc, v194, v200
	v_cmp_gt_i32_e64 s[42:43], v194, v241
	v_cndmask_b32_e64 v105, v222, v105, s[40:41]
	v_cmp_le_i32_e64 s[40:41], v195, v200
	s_and_b64 vcc, vcc, s[42:43]
	v_cmp_gt_i32_e64 s[42:43], v195, v241
	v_add_u32_e32 v194, 17, v0
	s_and_b64 s[40:41], s[40:41], s[42:43]
	v_cndmask_b32_e32 v122, v222, v122, vcc
	v_add_u32_e32 v195, 49, v0
	v_cmp_le_i32_e32 vcc, v194, v200
	v_cmp_gt_i32_e64 s[42:43], v194, v241
	v_cndmask_b32_e64 v106, v222, v106, s[40:41]
	v_cmp_le_i32_e64 s[40:41], v195, v200
	s_and_b64 vcc, vcc, s[42:43]
	v_cmp_gt_i32_e64 s[42:43], v195, v241
	v_add_u32_e32 v194, 18, v0
	s_and_b64 s[40:41], s[40:41], s[42:43]
	v_cndmask_b32_e32 v123, v222, v123, vcc
	v_add_u32_e32 v195, 50, v0
	v_cmp_le_i32_e32 vcc, v194, v200
	v_cmp_gt_i32_e64 s[42:43], v194, v241
	v_cndmask_b32_e64 v107, v222, v107, s[40:41]
	v_cmp_le_i32_e64 s[40:41], v195, v200
	s_and_b64 vcc, vcc, s[42:43]
	v_cmp_gt_i32_e64 s[42:43], v195, v241
	v_add_u32_e32 v194, 19, v0
	s_and_b64 s[40:41], s[40:41], s[42:43]
	v_cndmask_b32_e32 v124, v222, v124, vcc
	v_add_u32_e32 v195, 51, v0
	v_cmp_le_i32_e32 vcc, v194, v200
	v_cmp_gt_i32_e64 s[42:43], v194, v241
	v_cndmask_b32_e64 v108, v222, v108, s[40:41]
	v_cmp_le_i32_e64 s[40:41], v195, v200
	s_and_b64 vcc, vcc, s[42:43]
	v_cmp_gt_i32_e64 s[42:43], v195, v241
	v_add_u32_e32 v194, 24, v0
	s_and_b64 s[40:41], s[40:41], s[42:43]
	v_cndmask_b32_e32 v125, v222, v125, vcc
	v_add_u32_e32 v195, 56, v0
	v_cmp_le_i32_e32 vcc, v194, v200
	v_cmp_gt_i32_e64 s[42:43], v194, v241
	v_cndmask_b32_e64 v109, v222, v109, s[40:41]
	v_cmp_le_i32_e64 s[40:41], v195, v200
	s_and_b64 vcc, vcc, s[42:43]
	v_cmp_gt_i32_e64 s[42:43], v195, v241
	v_add_u32_e32 v194, 25, v0
	s_and_b64 s[40:41], s[40:41], s[42:43]
	v_cndmask_b32_e32 v126, v222, v126, vcc
	v_add_u32_e32 v195, 57, v0
	v_cmp_le_i32_e32 vcc, v194, v200
	v_cmp_gt_i32_e64 s[42:43], v194, v241
	v_cndmask_b32_e64 v110, v222, v110, s[40:41]
	v_cmp_le_i32_e64 s[40:41], v195, v200
	s_and_b64 vcc, vcc, s[42:43]
	v_cmp_gt_i32_e64 s[42:43], v195, v241
	v_add_u32_e32 v194, 26, v0
	s_and_b64 s[40:41], s[40:41], s[42:43]
	v_cndmask_b32_e32 v127, v222, v127, vcc
	v_add_u32_e32 v195, 58, v0
	v_cmp_le_i32_e32 vcc, v194, v200
	v_cmp_gt_i32_e64 s[42:43], v194, v241
	v_cndmask_b32_e64 v111, v222, v111, s[40:41]
	v_cmp_le_i32_e64 s[40:41], v195, v200
	s_and_b64 vcc, vcc, s[42:43]
	v_cmp_gt_i32_e64 s[42:43], v195, v241
	v_add_u32_e32 v194, 27, v0
	s_and_b64 s[40:41], s[40:41], s[42:43]
	v_cndmask_b32_e32 v128, v222, v128, vcc
	v_add_u32_e32 v0, 59, v0
	v_cmp_le_i32_e32 vcc, v194, v200
	v_cmp_gt_i32_e64 s[42:43], v194, v241
	v_cndmask_b32_e64 v112, v222, v112, s[40:41]
	v_cmp_le_i32_e64 s[40:41], v0, v200
	s_and_b64 vcc, vcc, s[42:43]
	v_cmp_gt_i32_e64 s[42:43], v0, v241
	s_and_b64 s[40:41], s[40:41], s[42:43]
	v_cndmask_b32_e32 v129, v222, v129, vcc
	v_cndmask_b32_e64 v113, v222, v113, s[40:41]
.LBB0_416:
	s_cmp_eq_u32 s101, 0
	s_cbranch_scc1 .LBB0_418
	v_max3_f32 v0, v114, v115, v116
	v_max3_f32 v194, v117, v118, v119
	v_max3_f32 v195, v120, v121, v122
	v_max3_f32 v0, v0, v123, v124
	v_max3_f32 v194, v194, v125, v126
	v_max3_f32 v195, v195, v127, v128
	v_max3_f32 v0, v0, v194, v129
	v_max_f32_e32 v0, v0, v195
	v_max3_f32 v194, v98, v99, v100
	v_max3_f32 v195, v101, v102, v103
	v_max3_f32 v196, v104, v105, v106
	v_max3_f32 v194, v194, v107, v108
	v_max3_f32 v195, v195, v109, v110
	v_max3_f32 v196, v196, v111, v112
	v_max3_f32 v194, v194, v195, v113
	v_max3_f32 v0, v0, v194, v196
	v_mov_b32_e32 v194, v0
	s_nop 1
	v_permlane32_swap_b32_e32 v0, v194
	v_max_f32_e32 v0, v0, v194
	v_add_f32_e32 v0, v0, v212
	v_max_f32_e32 v0, v242, v0
	v_add_f32_e32 v194, 0x41000000, v242
	v_cmp_gt_f32_e32 vcc, v0, v194
	s_cbranch_vccz .Lmy_w_noslow
	v_sub_f32_e32 v194, v242, v0
	v_exp_f32_e32 v194, v194
	s_nop 0
	v_mul_f32_e32 v203, v203, v194
	v_pk_mul_f32 v[32:33], v[32:33], v[194:195] op_sel_hi:[1,0]
	v_pk_mul_f32 v[30:31], v[30:31], v[194:195] op_sel_hi:[1,0]
	v_pk_mul_f32 v[28:29], v[28:29], v[194:195] op_sel_hi:[1,0]
	v_pk_mul_f32 v[26:27], v[26:27], v[194:195] op_sel_hi:[1,0]
	v_pk_mul_f32 v[24:25], v[24:25], v[194:195] op_sel_hi:[1,0]
	v_pk_mul_f32 v[22:23], v[22:23], v[194:195] op_sel_hi:[1,0]
	v_pk_mul_f32 v[20:21], v[20:21], v[194:195] op_sel_hi:[1,0]
	v_pk_mul_f32 v[18:19], v[18:19], v[194:195] op_sel_hi:[1,0]
	v_pk_mul_f32 v[16:17], v[16:17], v[194:195] op_sel_hi:[1,0]
	v_pk_mul_f32 v[14:15], v[14:15], v[194:195] op_sel_hi:[1,0]
	v_pk_mul_f32 v[12:13], v[12:13], v[194:195] op_sel_hi:[1,0]
	v_pk_mul_f32 v[10:11], v[10:11], v[194:195] op_sel_hi:[1,0]
	v_pk_mul_f32 v[8:9], v[8:9], v[194:195] op_sel_hi:[1,0]
	v_pk_mul_f32 v[6:7], v[6:7], v[194:195] op_sel_hi:[1,0]
	v_pk_mul_f32 v[4:5], v[4:5], v[194:195] op_sel_hi:[1,0]
	v_pk_mul_f32 v[2:3], v[2:3], v[194:195] op_sel_hi:[1,0]
	v_mov_b32_e32 v242, v0
	v_cmp_lt_f32_e32 vcc, 0xf0a18f08, v0
	s_nop 1
	v_cndmask_b32_e32 v213, 0, v0, vcc
	v_sub_f32_e32 v226, v213, v212
	v_mov_b32_e32 v212, v213
	v_sub_f32_e32 v34, 0, v213
	v_sub_f32_e32 v35, 0, v213
	v_sub_f32_e32 v36, 0, v213
	v_sub_f32_e32 v37, 0, v213
	v_sub_f32_e32 v38, 0, v213
	v_sub_f32_e32 v39, 0, v213
	v_sub_f32_e32 v40, 0, v213
	v_sub_f32_e32 v41, 0, v213
	v_sub_f32_e32 v42, 0, v213
	v_sub_f32_e32 v43, 0, v213
	v_sub_f32_e32 v44, 0, v213
	v_sub_f32_e32 v45, 0, v213
	v_sub_f32_e32 v46, 0, v213
	v_sub_f32_e32 v47, 0, v213
	v_sub_f32_e32 v48, 0, v213
	v_sub_f32_e32 v49, 0, v213
	v_sub_f32_e32 v98, v98, v226
	v_sub_f32_e32 v99, v99, v226
	v_sub_f32_e32 v100, v100, v226
	v_sub_f32_e32 v101, v101, v226
	v_sub_f32_e32 v102, v102, v226
	v_sub_f32_e32 v103, v103, v226
	v_sub_f32_e32 v104, v104, v226
	v_sub_f32_e32 v105, v105, v226
	v_sub_f32_e32 v106, v106, v226
	v_sub_f32_e32 v107, v107, v226
	v_sub_f32_e32 v108, v108, v226
	v_sub_f32_e32 v109, v109, v226
	v_sub_f32_e32 v110, v110, v226
	v_sub_f32_e32 v111, v111, v226
	v_sub_f32_e32 v112, v112, v226
	v_sub_f32_e32 v113, v113, v226
	v_sub_f32_e32 v114, v114, v226
	v_sub_f32_e32 v115, v115, v226
	v_sub_f32_e32 v116, v116, v226
	v_sub_f32_e32 v117, v117, v226
	v_sub_f32_e32 v118, v118, v226
	v_sub_f32_e32 v119, v119, v226
	v_sub_f32_e32 v120, v120, v226
	v_sub_f32_e32 v121, v121, v226
	v_sub_f32_e32 v122, v122, v226
	v_sub_f32_e32 v123, v123, v226
	v_sub_f32_e32 v124, v124, v226
	v_sub_f32_e32 v125, v125, v226
	v_sub_f32_e32 v126, v126, v226
	v_sub_f32_e32 v127, v127, v226
	v_sub_f32_e32 v128, v128, v226
	v_sub_f32_e32 v129, v129, v226
.Lmy_w_noslow:
	v_cmp_gt_f32_e32 vcc, 0xf0a18f08, v242
	s_nop 1
	s_cmp_lg_u64 vcc, 0
	s_cselect_b32 s100, 1, 0
.LBB0_418:
	s_nop 1
	v_exp_f32_e32 v114, v114
	v_exp_f32_e32 v98, v98
	v_exp_f32_e32 v115, v115
	v_exp_f32_e32 v99, v99
	v_add_f32_e32 v196, v114, v98
	v_exp_f32_e32 v116, v116
	v_exp_f32_e32 v100, v100
	v_add_f32_e32 v195, v115, v99
	v_add_f32_e32 v196, v195, v196
	v_exp_f32_e32 v117, v117
	v_exp_f32_e32 v101, v101
	v_add_f32_e32 v195, v116, v100
	v_add_f32_e32 v196, v195, v196
	v_exp_f32_e32 v118, v118
	v_exp_f32_e32 v102, v102
	v_add_f32_e32 v195, v117, v101
	v_add_f32_e32 v196, v195, v196
	v_exp_f32_e32 v119, v119
	v_exp_f32_e32 v103, v103
	v_add_f32_e32 v195, v118, v102
	v_add_f32_e32 v196, v195, v196
	v_exp_f32_e32 v120, v120
	v_exp_f32_e32 v104, v104
	v_add_f32_e32 v195, v119, v103
	v_add_f32_e32 v196, v195, v196
	v_exp_f32_e32 v121, v121
	v_exp_f32_e32 v105, v105
	v_add_f32_e32 v195, v120, v104
	v_add_f32_e32 v196, v195, v196
	v_exp_f32_e32 v122, v122
	v_exp_f32_e32 v106, v106
	v_add_f32_e32 v195, v121, v105
	v_add_f32_e32 v196, v195, v196
	v_exp_f32_e32 v123, v123
	v_exp_f32_e32 v107, v107
	v_add_f32_e32 v195, v122, v106
	v_add_f32_e32 v196, v195, v196
	v_exp_f32_e32 v124, v124
	v_exp_f32_e32 v108, v108
	v_add_f32_e32 v195, v123, v107
	v_add_f32_e32 v196, v195, v196
	v_exp_f32_e32 v125, v125
	v_exp_f32_e32 v109, v109
	v_add_f32_e32 v195, v124, v108
	v_add_f32_e32 v196, v195, v196
	v_exp_f32_e32 v126, v126
	v_exp_f32_e32 v110, v110
	v_add_f32_e32 v195, v125, v109
	v_add_f32_e32 v196, v195, v196
	v_exp_f32_e32 v127, v127
	v_exp_f32_e32 v111, v111
	v_add_f32_e32 v195, v126, v110
	v_add_f32_e32 v196, v195, v196
	v_exp_f32_e32 v128, v128
	v_exp_f32_e32 v112, v112
	v_add_f32_e32 v195, v127, v111
	v_add_f32_e32 v196, v195, v196
	v_exp_f32_e32 v129, v129
	v_exp_f32_e32 v113, v113
	v_add_f32_e32 v195, v128, v112
	v_add_f32_e32 v196, v195, v196
	v_add_f32_e32 v195, v129, v113
	v_add_f32_e32 v196, v195, v196
	v_cmp_lt_f32_e32 vcc, 0x47800000, v196
	s_cbranch_vccnz .Lmy_rd_w
.Lmy_nrd_w:
	v_cvt_pk_bf16_f32 v208, v114, v115
	v_cvt_pk_bf16_f32 v209, v116, v117
	v_cvt_pk_bf16_f32 v210, v118, v119
	v_cvt_pk_bf16_f32 v211, v120, v121
	v_cvt_pk_bf16_f32 v105, v104, v105
	v_cvt_pk_bf16_f32 v104, v102, v103
	s_waitcnt lgkmcnt(0)
	v_mfma_f32_32x32x16_bf16 v[2:17], v[190:193], v[208:211], v[2:17]
	v_cvt_pk_bf16_f32 v103, v100, v101
	v_cvt_pk_bf16_f32 v102, v98, v99
	v_mfma_f32_32x32x16_bf16 v[18:33], v[174:177], v[208:211], v[18:33]
	v_cvt_pk_bf16_f32 v98, v106, v107
	v_cvt_pk_bf16_f32 v99, v108, v109
	v_cvt_pk_bf16_f32 v100, v110, v111
	v_cvt_pk_bf16_f32 v101, v112, v113
	v_cvt_pk_bf16_f32 v106, v122, v123
	v_cvt_pk_bf16_f32 v107, v124, v125
	v_cvt_pk_bf16_f32 v108, v126, v127
	v_cvt_pk_bf16_f32 v109, v128, v129
	v_add_f32_e32 v203, v196, v203
	s_nop 0
	v_mfma_f32_32x32x16_bf16 v[2:17], v[186:189], v[106:109], v[2:17]
	v_mfma_f32_32x32x16_bf16 v[18:33], v[170:173], v[106:109], v[18:33]
	v_mfma_f32_32x32x16_bf16 v[2:17], v[182:185], v[102:105], v[2:17]
	v_mfma_f32_32x32x16_bf16 v[18:33], v[166:169], v[102:105], v[18:33]
	v_mfma_f32_32x32x16_bf16 v[2:17], v[178:181], v[98:101], v[2:17]
	v_mfma_f32_32x32x16_bf16 v[18:33], v[162:165], v[98:101], v[18:33]
	s_mov_b32 s101, s100
	s_add_i32 s94, s94, 1
	s_xor_b32 s14, s14, 1
	s_add_i32 s13, s13, 64
	s_add_u32 s0, s0, 0x2000
	s_addc_u32 s1, s1, 0
	s_andn2_b64 vcc, exec, s[44:45]
	s_cbranch_vccz .LBB0_235
	s_branch .LBB0_412

.LBB0_702:
	s_or_b64 exec, exec, s[14:15]
	s_waitcnt lgkmcnt(0)
	s_add_u32 s69, s86, s46
	s_addc_u32 s79, s87, s47
	s_movk_i32 s14, 0x104
	s_cmp_gt_i32 s53, -1
	s_mov_b32 s94, s53
	v_mul_lo_u32 v0, v37, s14
	s_cselect_b64 s[46:47], -1, 0
	s_lshl_b64 s[14:15], s[94:95], 3
	v_readlane_b32 s44, v253, 0
	v_readlane_b32 s45, v253, 1
	s_add_u32 s70, s44, s14
	s_addc_u32 s71, s45, s15
	s_ashr_i32 s55, s54, 31
	s_ashr_i32 s49, s48, 31
	v_lshl_add_u32 v0, v36, 2, v0
	s_cmp_eq_u32 s52, 0
	s_waitcnt vmcnt(0)
	ds_write2_b32 v0, v6, v7 offset1:1
	ds_write2_b32 v0, v8, v9 offset0:2 offset1:3
	v_add_u32_e32 v6, 0x1040, v0
	s_cselect_b64 s[44:45], -1, 0
	s_add_i32 s14, s68, 0xfffff540
	ds_write2_b32 v6, v2, v3 offset1:1
	v_add_u32_e32 v2, 0x1048, v0
	s_lshr_b32 s14, s14, 6
	ds_write2_b32 v2, v4, v5 offset1:1
	v_add_u32_e32 v2, 0x2080, v0
	s_cmp_gt_i32 s78, 42
	ds_write2_b32 v2, v14, v15 offset1:1
	v_add_u32_e32 v2, 0x2088, v0
	s_cselect_b32 s14, s14, s78
	ds_write2_b32 v2, v16, v17 offset1:1
	v_add_u32_e32 v2, 0x30c0, v0
	v_add_u32_e32 v0, 0x30c8, v0
	s_cselect_b32 s15, 64, 0
	s_lshl_b32 s14, s14, 7
	ds_write2_b32 v0, v12, v13 offset1:1
	v_lshlrev_b32_e32 v0, 3, v35
	s_or_b32 s14, s14, s15
	s_lshl_b64 s[52:53], s[48:49], 1
	v_ashrrev_i32_e32 v13, 3, v35
	v_and_b32_e32 v12, 56, v0
	s_add_u32 s52, s69, s52
	s_addc_u32 s53, s79, s53
	v_lshlrev_b32_e32 v0, 1, v12
	v_add_u32_e32 v14, s68, v13
	v_cndmask_b32_e64 v4, 0, 1, s[46:47]
	ds_write2_b32 v2, v10, v11 offset1:1
	v_lshl_add_u64 v[2:3], s[52:53], 0, v[0:1]
	v_cmp_gt_i32_e32 vcc, s13, v14
	v_mul_u32_u24_e32 v0, 0x104, v12
	v_cmp_ne_u32_e64 s[46:47], 1, v4
	s_waitcnt lgkmcnt(0)
	s_barrier
	s_and_saveexec_b64 s[52:53], vcc
	s_cbranch_execz .LBB0_706
	v_lshl_add_u32 v8, v13, 2, v0
	v_add_u32_e32 v10, 0x400, v8
	ds_read2_b32 v[4:5], v8 offset1:65
	ds_read2_b32 v[6:7], v8 offset0:130 offset1:195
	ds_read2_b32 v[8:9], v10 offset0:4 offset1:69
	ds_read2_b32 v[10:11], v10 offset0:134 offset1:199
	s_and_b64 vcc, exec, s[46:47]
	s_cbranch_vccnz .LBB0_705
	s_load_dwordx2 s[78:79], s[70:71], 0x0
	s_lshl_b64 s[80:81], s[54:55], 2
	v_lshlrev_b32_e32 v15, 2, v12
	s_waitcnt lgkmcnt(0)
	s_add_u32 s15, s78, s80
	s_addc_u32 s69, s79, s81
	v_readlane_b32 s78, v254, 44
	v_readlane_b32 s79, v254, 45
	s_add_u32 s15, s15, s78
	s_addc_u32 s69, s69, s79
	s_lshl_b64 s[78:79], s[48:49], 2
	s_add_u32 s78, s15, s78
	s_addc_u32 s79, s69, s79
	global_load_dwordx4 v[36:39], v15, s[78:79]
	global_load_dwordx4 v[40:43], v15, s[78:79] offset:16
	s_movk_i32 s80, 0x3000
	s_movk_i32 s81, 0x2000
	s_waitcnt vmcnt(1)
	v_pk_mul_f32 v[4:5], v[4:5], v[36:37]
	v_pk_mul_f32 v[6:7], v[6:7], v[38:39]
	s_waitcnt vmcnt(0)
	v_pk_mul_f32 v[8:9], v[8:9], v[40:41]
	v_pk_mul_f32 v[10:11], v[10:11], v[42:43]
	s_cmpk_lt_u32 s68, 0x400
	s_cbranch_scc0 .Lmy_nosc_b
	s_cmp_eq_u32 s94, 9
	s_cbranch_scc1 .Lmy_dosc_b
	s_cmp_eq_u32 s94, 1
	s_cbranch_scc0 .Lmy_nosc_b
	s_cmpk_lt_u32 s54, 0x800
	s_cbranch_scc0 .Lmy_nosc_b
.Lmy_dosc_b:
	v_mul_f32_e32 v4, 0x3e38aa3b, v4
	v_mul_f32_e32 v5, 0x3e38aa3b, v5
	v_mul_f32_e32 v6, 0x3e38aa3b, v6
	v_mul_f32_e32 v7, 0x3e38aa3b, v7
	v_mul_f32_e32 v8, 0x3e38aa3b, v8
	v_mul_f32_e32 v9, 0x3e38aa3b, v9
	v_mul_f32_e32 v10, 0x3e38aa3b, v10
	v_mul_f32_e32 v11, 0x3e38aa3b, v11

.LBB0_706:
	s_or_b64 exec, exec, s[52:53]
	v_add_u32_e32 v14, 32, v13
	v_add_u32_e32 v15, s68, v14
	v_cmp_gt_i32_e32 vcc, s13, v15
	s_and_saveexec_b64 s[52:53], vcc
	s_cbranch_execz .LBB0_659
	v_lshl_add_u32 v0, v13, 2, v0
	ds_read2_b32 v[4:5], v0 offset0:32 offset1:97
	ds_read2_b32 v[6:7], v0 offset0:162 offset1:227
	v_add_u32_e32 v0, 0x400, v0
	ds_read2_b32 v[8:9], v0 offset0:36 offset1:101
	ds_read2_b32 v[10:11], v0 offset0:166 offset1:231
	s_and_b64 vcc, exec, s[46:47]
	s_cbranch_vccnz .LBB0_658
	s_load_dwordx2 s[46:47], s[70:71], 0x0
	s_lshl_b64 s[54:55], s[54:55], 2
	v_lshlrev_b32_e32 v0, 2, v12
	s_waitcnt lgkmcnt(0)
	s_add_u32 s13, s46, s54
	s_addc_u32 s15, s47, s55
	v_readlane_b32 s46, v254, 44
	v_readlane_b32 s47, v254, 45
	s_add_u32 s13, s13, s46
	s_addc_u32 s15, s15, s47
	s_lshl_b64 s[46:47], s[48:49], 2
	s_add_u32 s46, s13, s46
	s_addc_u32 s47, s15, s47
	global_load_dwordx4 v[36:39], v0, s[46:47]
	global_load_dwordx4 v[40:43], v0, s[46:47] offset:16
	s_waitcnt vmcnt(1)
	v_pk_mul_f32 v[4:5], v[4:5], v[36:37]
	v_pk_mul_f32 v[6:7], v[6:7], v[38:39]
	s_waitcnt vmcnt(0)
	v_pk_mul_f32 v[8:9], v[8:9], v[40:41]
	v_pk_mul_f32 v[10:11], v[10:11], v[42:43]
	s_cmpk_lt_u32 s68, 0x400
	s_cbranch_scc0 .Lmy_nosc_a
	s_cmp_eq_u32 s94, 9
	s_cbranch_scc1 .Lmy_dosc_a
	s_cmp_eq_u32 s94, 1
	s_cbranch_scc0 .Lmy_nosc_a
	s_cmpk_lt_u32 s54, 0x2000
	s_cbranch_scc0 .Lmy_nosc_a
